# attn A/B loops: back-edge bookkeeping rotated ahead of the barrier, m0 save/restore dropped around LDS-DMA, rescale flag set only on the rare path (fewer SALU on the max->PV chain and after the barrie
# speedup vs baseline: 1.0029x; 1.0001x over previous
; template<int THRL,bool WIN,int DM,int ODM,int DV,int QMODE> __device__ __forceinline__ void attn_unit(const bf16*Qp,const bf16*__restrict__ Kp,const bf16*__restrict__ Vp,bf16*Op,const int q0,const int t_lo,const int NT,const float sink2,char*shm,const float*qgain,const float*qtab,const int b0,const ...
;     ...
;     float v[4][8];
;     #pragma unroll
;     for(int d0=0;d0<4;++d0){
;       #pragma unroll
;       for(int e=0;e<8;++e)v[d0][e]=__builtin_bit_cast(float,((unsigned)(unsigned short)qr[d0][e])<<16);}
;     const int bp=(lane^32)<<2;
;     if constexpr(QMODE==1){
;       float ss=0.f;
;       #pragma unroll
;       for(int d0=0;d0<4;++d0){
;         #pragma unroll
;         for(int e=0;e<8;++e)ss+=v[d0][e]*v[d0][e];}
;       ss+=__builtin_bit_cast(float,__builtin_amdgcn_ds_bpermute(bp,__builtin_bit_cast(int,ss)));
;       const float rn=__builtin_amdgcn_rsqf(ss*(1.f/64.f)+1e-6f);
;       const int trow=qpos>>6,tcol=qpos&63;
;       #pragma unroll
;       for(int d0=0;d0<4;++d0){ const f32x4_t g0=*(const f32x4_t*)(qgain+16*d0+8*hi),g1=*(const f32x4_t*)(qgain+16*d0+8*hi+4);
;         const float g[8]={g0.x,g0.y,g0.z,g0.w,g1.x,g1.y,g1.z,g1.w};
;         #pragma unroll
;         for(int e=0;e<8;++e)v[d0][e]=(v[d0][e]*rn)*g[e];}
.LBB0_382:
	v_lshlrev_b32_e32 v1, 2, v18
	v_or_b32_e32 v18, s13, v205
	v_add_u32_e32 v22, s80, v18
	v_lshlrev_b32_e32 v193, 4, v206
	v_lshlrev_b32_e32 v18, 5, v22
	s_movk_i32 s4, 0x7e0
	v_and_or_b32 v18, v18, s4, v193
	v_ashrrev_i32_e32 v22, 1, v22
	s_movk_i32 s4, 0xffe0
	v_and_or_b32 v22, v22, s4, v193
	v_ashrrev_i32_e32 v23, 31, v22
	v_lshlrev_b32_e32 v18, 2, v18
	v_lshl_add_u64 v[100:101], v[22:23], 2, s[10:11]
	global_load_dwordx4 v[76:79], v1, s[72:73] offset:208
	global_load_dwordx4 v[26:29], v1, s[72:73] offset:144
	global_load_dwordx4 v[30:33], v1, s[72:73] offset:128
	global_load_dwordx4 v[80:83], v1, s[72:73] offset:192
	global_load_dwordx4 v[34:37], v18, s[10:11] offset:48
	global_load_dwordx4 v[38:41], v18, s[10:11] offset:32
	global_load_dwordx4 v[42:45], v18, s[10:11] offset:16
	s_nop 0
	global_load_dwordx4 v[18:21], v18, s[10:11]
	s_nop 0
	global_load_dwordx4 v[58:61], v1, s[72:73] offset:16
	global_load_dwordx4 v[84:87], v1, s[72:73] offset:80
	global_load_dwordx4 v[22:25], v[100:101], off offset:48
	global_load_dwordx4 v[54:57], v[100:101], off offset:32
	global_load_dwordx4 v[88:91], v1, s[72:73]
	global_load_dwordx4 v[92:95], v1, s[72:73] offset:64
	v_lshlrev_b32_e32 v96, 2, v203
	v_xor_b32_e32 v1, 0x80, v96
	global_load_dwordx4 v[96:99], v[100:101], off
	s_nop 0
	global_load_dwordx4 v[100:103], v[100:101], off offset:16
	s_waitcnt vmcnt(19)
	v_and_b32_e32 v153, 0xffff0000, v47
	v_lshlrev_b32_e32 v154, 16, v47
	v_and_b32_e32 v161, 0xffff0000, v46
	s_waitcnt vmcnt(18)
	v_lshlrev_b32_e32 v160, 16, v50
	v_and_b32_e32 v47, 0xffff0000, v50
	v_lshlrev_b32_e32 v46, 16, v46
	v_lshlrev_b32_e32 v152, 16, v51
	v_and_b32_e32 v155, 0xffff0000, v51
	v_pk_mul_f32 v[50:51], v[46:47], v[46:47]
	v_pk_mul_f32 v[162:163], v[160:161], v[160:161]
	v_pk_mul_f32 v[156:157], v[154:155], v[154:155]
	v_add_f32_e32 v50, v50, v163
	v_and_b32_e32 v133, 0xffff0000, v49
	v_lshlrev_b32_e32 v134, 16, v49
	v_and_b32_e32 v145, 0xffff0000, v48
	v_and_b32_e32 v49, 0xffff0000, v52
	v_lshlrev_b32_e32 v48, 16, v48
	v_pk_mul_f32 v[158:159], v[152:153], v[152:153]
	v_add_f32_e32 v50, v156, v50
	v_lshlrev_b32_e32 v132, 16, v53
	v_and_b32_e32 v135, 0xffff0000, v53
	v_lshlrev_b32_e32 v144, 16, v52
	v_pk_mul_f32 v[52:53], v[48:49], v[48:49]
	v_add_f32_e32 v50, v159, v50
	v_pk_mul_f32 v[146:147], v[144:145], v[144:145]
	v_add_f32_e32 v50, v52, v50
	v_pk_mul_f32 v[136:137], v[134:135], v[134:135]
	v_add_f32_e32 v50, v147, v50
	v_pk_mul_f32 v[138:139], v[132:133], v[132:133]
	v_add_f32_e32 v50, v136, v50
	v_add_f32_e32 v50, v139, v50
	v_add_f32_e32 v50, v162, v50
	v_add_f32_e32 v50, v51, v50
	v_add_f32_e32 v50, v158, v50
	v_add_f32_e32 v50, v157, v50
	v_add_f32_e32 v50, v146, v50
	v_add_f32_e32 v50, v53, v50
	v_add_f32_e32 v50, v138, v50
	s_waitcnt vmcnt(17)
	v_lshlrev_b32_e32 v114, 16, v62
	v_add_f32_e32 v50, v137, v50
	v_and_b32_e32 v113, 0xffff0000, v62
	v_fmac_f32_e32 v50, v114, v114
	v_lshlrev_b32_e32 v110, 16, v63
	v_fmac_f32_e32 v50, v113, v113
	v_and_b32_e32 v109, 0xffff0000, v63
	v_fmac_f32_e32 v50, v110, v110
	v_lshlrev_b32_e32 v106, 16, v64
	v_fmac_f32_e32 v50, v109, v109
	v_and_b32_e32 v105, 0xffff0000, v64
	v_fmac_f32_e32 v50, v106, v106
	v_lshlrev_b32_e32 v72, 16, v65
	s_waitcnt vmcnt(16)
	v_lshlrev_b32_e32 v112, 16, v66
	v_and_b32_e32 v115, 0xffff0000, v66
	v_fmac_f32_e32 v50, v105, v105
	v_lshlrev_b32_e32 v70, 16, v69
	v_and_b32_e32 v71, 0xffff0000, v65
	v_and_b32_e32 v73, 0xffff0000, v69
	v_lshlrev_b32_e32 v104, 16, v68
	v_and_b32_e32 v107, 0xffff0000, v68
	v_pk_mov_b32 v[68:69], v[114:115], v[112:113] op_sel:[1,0]
	v_fmac_f32_e32 v50, v72, v72
	v_lshlrev_b32_e32 v108, 16, v67
	v_and_b32_e32 v111, 0xffff0000, v67
	v_pk_mul_f32 v[122:123], v[68:69], v[68:69]
	v_fmac_f32_e32 v50, v71, v71
	v_pk_mov_b32 v[66:67], v[110:111], v[108:109] op_sel:[1,0]
	v_add_f32_e32 v50, v123, v50
	v_pk_mul_f32 v[120:121], v[66:67], v[66:67]
	v_add_f32_e32 v50, v122, v50
	v_pk_mov_b32 v[64:65], v[106:107], v[104:105] op_sel:[1,0]
	v_add_f32_e32 v50, v121, v50
	v_pk_mul_f32 v[118:119], v[64:65], v[64:65]
	v_add_f32_e32 v50, v120, v50
	v_pk_mov_b32 v[62:63], v[72:73], v[70:71] op_sel:[1,0]
	v_add_f32_e32 v50, v119, v50
	v_pk_mul_f32 v[116:117], v[62:63], v[62:63]
	v_add_f32_e32 v50, v118, v50
	v_add_f32_e32 v50, v117, v50
	v_add_f32_e32 v53, v116, v50
	ds_bpermute_b32 v1, v1, v53
	s_waitcnt vmcnt(2)
	v_mov_b32_e32 v50, v94
	v_mov_b32_e32 v141, v61
	v_mov_b32_e32 v61, v87
	v_mov_b32_e32 v120, v92
	s_waitcnt lgkmcnt(0)
	v_add_f32_e32 v1, v53, v1
	v_fmamk_f32 v1, v1, 0x3c800000, v241
	v_rsq_f32_e32 v94, v1
	v_mov_b32_e32 v121, v89
	v_mov_b32_e32 v89, v93
	v_mov_b32_e32 v124, v78
	v_pk_mul_f32 v[92:93], v[94:95], v[134:135] op_sel_hi:[0,1]
	v_mov_b32_e32 v125, v29
	v_mov_b32_e32 v29, v79
	v_mov_b32_e32 v78, v76
	v_mov_b32_e32 v79, v27
	v_mov_b32_e32 v27, v77
	v_mov_b32_e32 v76, v82
	v_mov_b32_e32 v77, v33
	v_mov_b32_e32 v33, v83
	v_mov_b32_e32 v82, v80
	v_mov_b32_e32 v83, v31
	v_pk_mul_f32 v[60:61], v[60:61], v[92:93]
	v_pk_mul_f32 v[92:93], v[94:95], v[112:113] op_sel_hi:[0,1]
	v_mov_b32_e32 v31, v81
	v_pk_mul_f32 v[82:83], v[92:93], v[82:83]
	v_pk_mul_f32 v[92:93], v[94:95], v[114:115] op_sel_hi:[0,1]
	v_pk_mul_f32 v[92:93], v[92:93], v[30:31]
	v_pk_mul_f32 v[30:31], v[94:95], v[108:109] op_sel_hi:[0,1]
	v_pk_mul_f32 v[76:77], v[30:31], v[76:77]
	v_pk_mul_f32 v[30:31], v[94:95], v[110:111] op_sel_hi:[0,1]
	v_pk_mul_f32 v[108:109], v[30:31], v[32:33]
	v_pk_mul_f32 v[30:31], v[94:95], v[104:105] op_sel_hi:[0,1]
	v_pk_mul_f32 v[78:79], v[30:31], v[78:79]
	v_pk_mul_f32 v[30:31], v[94:95], v[106:107] op_sel_hi:[0,1]
	v_pk_mul_f32 v[104:105], v[30:31], v[26:27]
	v_pk_mul_f32 v[26:27], v[94:95], v[70:71] op_sel_hi:[0,1]
	v_pk_mul_f32 v[118:119], v[94:95], v[160:161] op_sel_hi:[0,1]
	v_pk_mul_f32 v[46:47], v[94:95], v[46:47] op_sel_hi:[0,1]
	v_pk_mul_f32 v[70:71], v[26:27], v[124:125]
	v_pk_mul_f32 v[26:27], v[94:95], v[72:73] op_sel_hi:[0,1]
	v_mov_b32_e32 v51, v91
	v_pk_mul_f32 v[118:119], v[120:121], v[118:119]
	v_pk_mul_f32 v[46:47], v[88:89], v[46:47]
	v_pk_mul_f32 v[88:89], v[94:95], v[152:153] op_sel_hi:[0,1]
	v_pk_mul_f32 v[72:73], v[26:27], v[28:29]
	s_waitcnt vmcnt(1)
; __device__ __forceinline__ unsigned cvtpk_s(float lo,float hi){f32x2_t v={lo,hi};bf16x2_t b=__builtin_convertvector(v,bf16x2_t);return __builtin_bit_cast(unsigned,b);}
; #define WAIT_BAR(N) asm volatile("s_waitcnt vmcnt(" #N ") lgkmcnt(0)\n\ts_barrier":::"memory")
;   #define CMASK(P0,P1,t) do{ if constexpr(WIN){ wmask(P0,P1,(t_lo+(t))*KVBLK+4*hi,qpos); } }while(0)
; template<int THRL,bool WIN,int DM,int ODM,int DV,int QMODE> __device__ __forceinline__ void attn_unit(const bf16*Qp,const bf16*__restrict__ Kp,const bf16*__restrict__ Vp,bf16*Op,const int q0,const int t_lo,const int NT,const float sink2,char*shm,const float*qgain,const float*qtab,const int b0,const ...
;     ...
;       for(int h2=0;h2<2;++h2){ const float*tb=qtab+((h2==0?trow:tcol)*16+8*hi)*2;
;         const f32x4_t c0=*(const f32x4_t*)(tb),c1=*(const f32x4_t*)(tb+4),c2=*(const f32x4_t*)(tb+8),c3=*(const f32x4_t*)(tb+12);
;         const float cc[8]={c0.x,c0.z,c1.x,c1.z,c2.x,c2.z,c3.x,c3.z},sn[8]={c0.y,c0.w,c1.y,c1.w,c2.y,c2.w,c3.y,c3.w};
;         #pragma unroll
;         for(int e=0;e<8;++e){ const float x1=v[2*h2][e],x2=v[2*h2+1][e]; v[2*h2][e]=x1*cc[e]-x2*sn[e]; v[2*h2+1][e]=x2*cc[e]+x1*sn[e]; } }
;     } else {
;       const float*tb=qtab+(size_t)qpos*16;
;       const f32x4_t c0=*(const f32x4_t*)(tb),c1=*(const f32x4_t*)(tb+4),c2=*(const f32x4_t*)(tb+8),c3=*(const f32x4_t*)(tb+12);
;       const float cc[8]={c0.x,c0.z,c1.x,c1.z,c2.x,c2.z,c3.x,c3.z},sn[8]={c0.y,c0.w,c1.y,c1.w,c2.y,c2.w,c3.y,c3.w};
;       const float sg=hi?1.f:-1.f;
;       #pragma unroll
;       for(int e=0;e<8;++e){ const float p=__builtin_bit_cast(float,__builtin_amdgcn_ds_bpermute(bp,__builtin_bit_cast(int,v[0][e]))); v[0][e]=v[0][e]*cc[e]+sg*(p*sn[e]); }
;     }
;     #pragma unroll
;     for(int d0=0;d0<4;++d0){ u32x4 w; w[0]=cvtpk_s(v[d0][0]*QS,v[d0][1]*QS); w[1]=cvtpk_s(v[d0][2]*QS,v[d0][3]*QS); w[2]=cvtpk_s(v[d0][4]*QS,v[d0][5]*QS); w[3]=cvtpk_s(v[d0][6]*QS,v[d0][7]*QS);
;       qr[d0]=__builtin_bit_cast(bf16x8,w); }
;   }
;   WAIT_BAR(3);
;   qkt(pA0,pA1,Kbase+s0,qr,negm,r32,hi);asm volatile("s_nop 15\n\ts_nop 7":"+v"(pA0),"+v"(pA1));CMASK(pA0,pA1,0);
	v_mov_b32_e32 v28, v96
	v_mov_b32_e32 v29, v99
	v_mov_b32_e32 v91, v95
	s_waitcnt vmcnt(0)
	v_mov_b32_e32 v116, v100
	v_mov_b32_e32 v117, v103
	v_pk_mul_f32 v[50:51], v[50:51], v[88:89]
	v_pk_mul_f32 v[88:89], v[94:95], v[154:155] op_sel_hi:[0,1]
	v_mov_b32_e32 v26, v97
	v_mov_b32_e32 v27, v98
	v_pk_mul_f32 v[28:29], v[118:119], v[28:29]
	v_mov_b32_e32 v52, v101
	v_mov_b32_e32 v53, v102
	v_pk_mul_f32 v[88:89], v[90:91], v[88:89]
	v_pk_fma_f32 v[26:27], v[46:47], v[26:27], v[28:29]
	v_pk_mul_f32 v[28:29], v[50:51], v[116:117]
	v_mov_b32_e32 v107, v98
	v_pk_fma_f32 v[28:29], v[88:89], v[52:53], v[28:29]
	v_mov_b32_e32 v53, v119
	v_mov_b32_e32 v119, v47
	v_mov_b32_e32 v98, v97
	v_mov_b32_e32 v148, v84
	v_mov_b32_e32 v149, v59
	v_pk_mul_f32 v[90:91], v[94:95], v[144:145] op_sel_hi:[0,1]
	v_mov_b32_e32 v52, v46
	v_mov_b32_e32 v106, v96
	v_pk_mul_f32 v[46:47], v[118:119], v[98:99]
	v_mov_b32_e32 v59, v85
	v_mov_b32_e32 v150, v54
	v_mov_b32_e32 v151, v57
	v_pk_mul_f32 v[90:91], v[148:149], v[90:91]
	v_pk_mul_f32 v[48:49], v[94:95], v[48:49] op_sel_hi:[0,1]
	v_pk_fma_f32 v[46:47], v[52:53], v[106:107], v[46:47] neg_lo:[0,0,1] neg_hi:[0,0,1]
	v_mov_b32_e32 v130, v42
	v_mov_b32_e32 v131, v45
	v_mov_b32_e32 v84, v55
	v_mov_b32_e32 v85, v56
	v_pk_mul_f32 v[48:49], v[58:59], v[48:49]
	v_pk_mul_f32 v[30:31], v[90:91], v[150:151]
	v_pk_mul_f32 v[46:47], v[46:47], s[50:51] op_sel_hi:[1,0]
	v_pk_fma_f32 v[30:31], v[48:49], v[84:85], v[30:31]
	v_pk_mul_f32 v[84:85], v[76:77], v[130:131]
	v_cvt_pk_bf16_f32 v130, v46, v47
	v_mov_b32_e32 v47, v51
	v_mov_b32_e32 v53, v102
	v_mov_b32_e32 v51, v89
	v_mov_b32_e32 v102, v101
	v_mov_b32_e32 v46, v88
	v_mov_b32_e32 v52, v100
	v_pk_mul_f32 v[50:51], v[50:51], v[102:103]
	v_mov_b32_e32 v140, v86
	v_pk_fma_f32 v[46:47], v[46:47], v[52:53], v[50:51] neg_lo:[0,0,1] neg_hi:[0,0,1]
	v_mov_b32_e32 v51, v56
	v_pk_mul_f32 v[46:47], v[46:47], s[50:51] op_sel_hi:[1,0]
	v_mov_b32_e32 v56, v55
	v_cvt_pk_bf16_f32 v131, v46, v47
	v_mov_b32_e32 v47, v91
	v_mov_b32_e32 v91, v49
	v_mov_b32_e32 v46, v48
	v_mov_b32_e32 v50, v54
	v_pk_mul_f32 v[48:49], v[90:91], v[56:57]
	v_pk_mul_f32 v[58:59], v[94:95], v[132:133] op_sel_hi:[0,1]
	v_pk_fma_f32 v[46:47], v[46:47], v[50:51], v[48:49] neg_lo:[0,0,1] neg_hi:[0,0,1]
	v_mov_b32_e32 v142, v22
	v_mov_b32_e32 v143, v25
	v_pk_mul_f32 v[58:59], v[140:141], v[58:59]
	v_pk_mul_f32 v[46:47], v[46:47], s[50:51] op_sel_hi:[1,0]
	s_and_b32 s2, s2, 0x3fffffc0
	v_mov_b32_e32 v87, v24
	v_pk_mul_f32 v[32:33], v[58:59], v[142:143]
	v_cvt_pk_bf16_f32 v132, v46, v47
	v_mov_b32_e32 v47, v59
	v_mov_b32_e32 v49, v24
	v_mov_b32_e32 v59, v61
	v_mov_b32_e32 v24, v23
	s_lshl_b32 s2, s2, 2
	v_mov_b32_e32 v86, v23
	v_mov_b32_e32 v46, v60
	v_mov_b32_e32 v48, v22
	v_pk_mul_f32 v[22:23], v[58:59], v[24:25]
	s_add_i32 s25, s2, 0
	v_pk_fma_f32 v[22:23], v[46:47], v[48:49], v[22:23] neg_lo:[0,0,1] neg_hi:[0,0,1]
	s_add_i32 s25, s25, 0x12000
	v_pk_mul_f32 v[22:23], v[22:23], s[50:51] op_sel_hi:[1,0]
	s_and_b64 s[4:5], s[6:7], exec
	v_cvt_pk_bf16_f32 v133, v22, v23
	v_pk_mul_f32 v[22:23], v[26:27], s[50:51] op_sel_hi:[1,0]
	v_lshlrev_b32_e32 v164, 10, v206
	v_lshlrev_b32_e32 v165, 4, v205
	s_cselect_b32 s24, 0x80, 64
	v_cvt_pk_bf16_f32 v122, v22, v23
	v_pk_mul_f32 v[22:23], v[28:29], s[50:51] op_sel_hi:[1,0]
	s_add_i32 s2, s20, 0
	v_pk_fma_f32 v[32:33], v[60:61], v[86:87], v[32:33]
	v_cvt_pk_bf16_f32 v123, v22, v23
	v_pk_mul_f32 v[22:23], v[30:31], s[50:51] op_sel_hi:[1,0]
	s_waitcnt vmcnt(3) lgkmcnt(0)
	s_barrier
	v_add3_u32 v1, s2, v164, v165
	v_mov_b32_e32 v80, v18
	v_mov_b32_e32 v81, v21
	v_cvt_pk_bf16_f32 v124, v22, v23
	v_pk_mul_f32 v[22:23], v[32:33], s[50:51] op_sel_hi:[1,0]
	ds_read_b128 v[46:49], v1 offset:512
	ds_read_b128 v[50:53], v1
	v_mov_b32_e32 v69, v20
	v_pk_mul_f32 v[80:81], v[82:83], v[80:81]
	v_cvt_pk_bf16_f32 v125, v22, v23
	v_mov_b32_e32 v23, v83
	v_mov_b32_e32 v25, v20
	v_mov_b32_e32 v83, v93
	v_mov_b32_e32 v20, v19
	v_mov_b32_e32 v68, v19
	v_mov_b32_e32 v22, v92
	v_mov_b32_e32 v24, v18
	v_pk_mul_f32 v[18:19], v[82:83], v[20:21]
	v_mov_b32_e32 v67, v44
	v_pk_fma_f32 v[18:19], v[22:23], v[24:25], v[18:19] neg_lo:[0,0,1] neg_hi:[0,0,1]
	v_mov_b32_e32 v55, v77
	v_pk_mul_f32 v[18:19], v[18:19], s[50:51] op_sel_hi:[1,0]
	v_mov_b32_e32 v57, v44
	v_mov_b32_e32 v77, v109
	v_mov_b32_e32 v44, v43
	v_mov_b32_e32 v66, v43
	v_cvt_pk_bf16_f32 v138, v18, v19
	v_mov_b32_e32 v54, v108
	v_mov_b32_e32 v56, v42
	s_waitcnt lgkmcnt(0)
	v_mfma_f32_32x32x16_bf16 v[18:33], v[50:53], v[130:133], v[2:17]
	v_mul_f32_e64 v42, v76, v44
	v_mul_f32_e64 v43, v77, v45
	v_mov_b32_e32 v128, v38
	v_fma_f32 v42, v54, v56, -v42
	v_fma_f32 v43, v55, v57, -v43
	v_mov_b32_e32 v129, v41
	v_pk_mul_f32 v[42:43], v[42:43], s[50:51] op_sel_hi:[1,0]
	v_mov_b32_e32 v65, v40
	v_cvt_pk_bf16_f32 v139, v42, v43
	v_mfma_f32_32x32x16_bf16 v[2:17], v[46:49], v[130:133], v[2:17]
	ds_read_b128 v[42:45], v1 offset:2560
	ds_read_b128 v[50:53], v1 offset:2048
	v_mul_f32_e64 v86, v78, v128
	v_mul_f32_e64 v87, v79, v129
	v_mov_b32_e32 v55, v79
	v_mov_b32_e32 v47, v40
	v_mov_b32_e32 v79, v105
	v_mov_b32_e32 v40, v39
	v_mov_b32_e32 v64, v39
	v_mov_b32_e32 v54, v104
	v_mov_b32_e32 v46, v38
	v_pk_mul_f32 v[38:39], v[78:79], v[40:41]
	s_waitcnt lgkmcnt(0)
; __device__ __forceinline__ float max3f(float a,float b,float c){float r;asm("v_max3_f32 %0, %1, %2, %3":"=v"(r):"v"(a),"v"(b),"v"(c));return r;}
; __device__ __forceinline__ float max2f(float a,float b){float r;asm("v_max_f32_e32 %0, %1, %2":"=v"(r):"v"(a),"v"(b));return r;}
; #define WAIT_BAR(N) asm volatile("s_waitcnt vmcnt(" #N ") lgkmcnt(0)\n\ts_barrier":::"memory")
;   #define DMA_K(t,slot) glds16(ksrc+(long)(t)*KVBLK*DM,(unsigned)__builtin_amdgcn_readfirstlane(kdst+(slot)))
;   #define DMA_V(t,slot) do{ glds16(vsrc+(long)(t)*KVBLK*DM,(unsigned)__builtin_amdgcn_readfirstlane(vdst+VM*(slot))); \
;     if constexpr(DV==128){ glds16(vsrc+64+(long)(t)*KVBLK*DM,(unsigned)__builtin_amdgcn_readfirstlane(vdst+VM*(slot)+8192)); } }while(0)
;   #define WAIT_KV() do{ if constexpr(DV==128){WAIT_BAR(3);} else {WAIT_BAR(2);} }while(0)
;   #define CMASK(P0,P1,t) do{ if constexpr(WIN){ wmask(P0,P1,(t_lo+(t))*KVBLK+4*hi,qpos); } }while(0)
;   #define ROT() do{sl_prev=sl_cur;sl_cur=sl_next;sl_next=(sl_next==(NSLOT-1)*SLOTB)?0:sl_next+SLOTB;}while(0)
; __device__ __forceinline__ float rowmax(const f32x16&p0,const f32x16&p1){
;   float a=max3f(p0[0],p0[1],p1[0]),b=max3f(p0[2],p0[3],p1[1]);a=max3f(a,p1[2],p1[3]);
;   #pragma unroll
;   for(int r=4;r<16;r+=4){a=max3f(a,p0[r],p0[r+1]);b=max3f(b,p0[r+2],p0[r+3]);a=max3f(a,p1[r],p1[r+1]);b=max3f(b,p1[r+2],p1[r+3]);}
;   const float m=max2f(a,b);
;   auto rr=__builtin_amdgcn_permlane32_swap(__float_as_uint(m),__float_as_uint(m),false,false);
;   return max2f(__uint_as_float(rr[0]),__uint_as_float(rr[1]));
; template<int THRL,bool WIN,int DM,int ODM,int DV,int QMODE> __device__ __forceinline__ void attn_unit(const bf16*Qp,const bf16*__restrict__ Kp,const bf16*__restrict__ Vp,bf16*Op,const int q0,const int t_lo,const int NT,const float sink2,char*shm,const float*qgain,const float*qtab,const int b0,const ...
;     ...
;   WAIT_BAR(3);
;   qkt(pA0,pA1,Kbase+s0,qr,negm,r32,hi);asm volatile("s_nop 15\n\ts_nop 7":"+v"(pA0),"+v"(pA1));CMASK(pA0,pA1,0);
;   START(pA0,pA1);
;   _Pragma("unroll") for(int r=0;r<16;++r)pA1[r]=__builtin_amdgcn_exp2f(pA1[r]);
;   WAIT_BAR(0);
;   DMA_K(3,s0);DMA_V(1,s1);
;   ROT();
;   kload8(kf,kp0+sl_cur);
;   WAIT_KV();
	v_mfma_f32_32x32x16_bf16 v[18:33], v[50:53], v[122:125], v[18:33]
	v_fma_f32 v38, v54, v46, -v38
	v_fma_f32 v39, v55, v47, -v39
	v_mov_b32_e32 v126, v34
	v_mov_b32_e32 v127, v37
	v_mul_f32_e64 v38, v38, s50
	v_mul_f32_e64 v39, v39, s50
	v_mov_b32_e32 v63, v36
	v_pk_mul_f32 v[94:95], v[70:71], v[126:127]
	v_cvt_pk_bf16_f32 v140, v38, v39
	v_mfma_f32_32x32x16_bf16 v[2:17], v[42:45], v[122:125], v[2:17]
	v_mov_b32_e32 v51, v71
	ds_read_b128 v[38:41], v1 offset:4608
	ds_read_b128 v[46:49], v1 offset:4096
	v_mov_b32_e32 v53, v36
	v_mov_b32_e32 v71, v73
	v_mov_b32_e32 v36, v35
	v_mov_b32_e32 v62, v35
	v_mov_b32_e32 v50, v72
	v_mov_b32_e32 v52, v34
	v_pk_mul_f32 v[34:35], v[70:71], v[36:37]
	v_lshlrev_b32_e32 v75, 1, v74
	v_pk_fma_f32 v[34:35], v[50:51], v[52:53], v[34:35] neg_lo:[0,0,1] neg_hi:[0,0,1]
	v_pk_fma_f32 v[50:51], v[72:73], v[62:63], v[94:95]
	v_pk_mul_f32 v[34:35], v[34:35], s[50:51] op_sel_hi:[1,0]
	v_and_b32_e32 v195, 32, v75
	v_cvt_pk_bf16_f32 v141, v34, v35
	v_pk_fma_f32 v[34:35], v[92:93], v[68:69], v[80:81]
	v_add3_u32 v211, 0, v164, v165
	s_waitcnt lgkmcnt(0)
	v_mfma_f32_32x32x16_bf16 v[18:33], v[46:49], v[138:141], v[18:33]
	v_fma_f32 v46, v108, v66, v84
	v_fma_f32 v47, v109, v67, v85
	v_mul_f32_e64 v52, v34, s50
	v_mul_f32_e64 v53, v35, s50
	ds_read_b128 v[34:37], v1 offset:6656
	ds_read_b128 v[42:45], v1 offset:6144
	v_pk_fma_f32 v[48:49], v[104:105], v[64:65], v[86:87]
	v_lshlrev_b32_e32 v1, 4, v74
	v_cvt_pk_bf16_f32 v134, v52, v53
	v_and_b32_e32 v1, 0xc0, v1
	v_mfma_f32_32x32x16_bf16 v[2:17], v[38:41], v[138:141], v[2:17]
	v_mul_f32_e64 v38, v46, s50
	v_mul_f32_e64 v39, v47, s50
	v_lshl_or_b32 v207, v206, 8, v1
	v_cvt_pk_bf16_f32 v135, v38, v39
	v_mul_f32_e64 v38, v48, s50
	v_mul_f32_e64 v39, v49, s50
	v_add_u32_e32 v1, 0, v195
	v_cvt_pk_bf16_f32 v136, v38, v39
	v_pk_mul_f32 v[38:39], v[50:51], s[50:51] op_sel_hi:[1,0]
	v_add3_u32 v210, v1, v191, v207
	v_cvt_pk_bf16_f32 v137, v38, v39
	s_add_i32 s2, s22, s20
	s_mov_b32 s13, 1
	s_waitcnt lgkmcnt(0)
	v_mfma_f32_32x32x16_bf16 v[18:33], v[42:45], v[134:137], v[18:33]
	s_mov_b32 s26, 5
	s_add_i32 s15, s24, -5
	v_lshl_add_u32 v208, v205, 2, s25
	v_lshl_add_u64 v[182:183], v[198:199], 0, s[56:57]
	v_lshl_add_u64 v[184:185], v[196:197], 0, s[58:59]
	v_lshl_add_u64 v[200:201], v[198:199], 0, s[60:61]
	v_mov_b32_e32 v212, 0
	v_mfma_f32_32x32x16_bf16 v[2:17], v[34:37], v[134:137], v[2:17]
	s_nop 15
	s_nop 7
	s_nop 0
	v_max3_f32 v1, v18, v19, v2
	v_max3_f32 v34, v20, v21, v3
	s_nop 0
	v_max3_f32 v1, v1, v4, v5
	v_max3_f32 v34, v34, v24, v25
	s_nop 0
	v_max3_f32 v1, v1, v22, v23
	v_max3_f32 v34, v34, v8, v9
	s_nop 0
	v_max3_f32 v1, v1, v6, v7
	v_max3_f32 v34, v34, v28, v29
	s_nop 0
	v_max3_f32 v1, v1, v26, v27
	v_max3_f32 v34, v34, v12, v13
	s_nop 0
	v_max3_f32 v1, v1, v10, v11
	v_max3_f32 v34, v34, v32, v33
	s_nop 0
	v_max3_f32 v1, v1, v30, v31
	v_max3_f32 v34, v34, v16, v17
	s_nop 0
	v_max3_f32 v1, v1, v14, v15
	s_nop 0
	v_max_f32_e32 v1, v1, v34
	s_nop 0
	v_mov_b32_e32 v34, v1
	s_nop 1
	v_permlane32_swap_b32_e32 v1, v34
	v_max_f32_e32 v1, v1, v34
	s_nop 0
	v_add_f32_e32 v209, v0, v1
	v_sub_f32_e32 v50, v2, v1
	v_sub_f32_e32 v51, v3, v1
	v_lshl_add_u64 v[2:3], v[196:197], 0, s[56:57]
	v_xor_b32_e32 v34, 0x80000000, v209
	v_mov_b32_e32 v35, v34
	v_mov_b32_e32 v36, v34
	v_mov_b32_e32 v37, v34
	v_mov_b32_e32 v38, v34
	v_mov_b32_e32 v39, v34
	v_mov_b32_e32 v40, v34
	v_mov_b32_e32 v41, v34
	v_mov_b32_e32 v42, v34
	v_mov_b32_e32 v43, v34
	v_mov_b32_e32 v44, v34
	v_mov_b32_e32 v45, v34
	v_mov_b32_e32 v46, v34
	v_mov_b32_e32 v47, v34
	v_mov_b32_e32 v48, v34
	v_mov_b32_e32 v49, v34
	s_waitcnt vmcnt(0) lgkmcnt(0)
	s_barrier
	s_mov_b32 s4, m0
	s_mov_b32 m0, s2
	s_nop 0
	global_load_lds_dwordx4 v[2:3], off
	s_mov_b32 m0, s4
	v_lshl_add_u64 v[2:3], v[198:199], 0, s[54:55]
	s_add_i32 s2, s23, s3
	s_mov_b32 s4, m0
	s_mov_b32 m0, s2
	s_nop 0
	global_load_lds_dwordx4 v[2:3], off
	s_mov_b32 m0, s4
	v_add_u32_e32 v2, s3, v211
	ds_read_b128 v[174:177], v2
	ds_read_b128 v[170:173], v2 offset:512
	ds_read_b128 v[166:169], v2 offset:2048
	ds_read_b128 v[162:165], v2 offset:2560
	ds_read_b128 v[158:161], v2 offset:4096
	ds_read_b128 v[154:157], v2 offset:4608
	ds_read_b128 v[150:153], v2 offset:6144
	ds_read_b128 v[146:149], v2 offset:6656
	v_sub_f32_e32 v18, v18, v1
	v_sub_f32_e32 v19, v19, v1
	v_sub_f32_e32 v20, v20, v1
	v_sub_f32_e32 v4, v4, v1
	v_sub_f32_e32 v21, v21, v1
	v_sub_f32_e32 v5, v5, v1
	v_sub_f32_e32 v22, v22, v1
	v_sub_f32_e32 v6, v6, v1
	v_sub_f32_e32 v23, v23, v1
	v_sub_f32_e32 v7, v7, v1
	v_sub_f32_e32 v24, v24, v1
	v_sub_f32_e32 v8, v8, v1
	v_sub_f32_e32 v25, v25, v1
	v_sub_f32_e32 v9, v9, v1
	v_sub_f32_e32 v26, v26, v1
	v_sub_f32_e32 v10, v10, v1
	v_sub_f32_e32 v27, v27, v1
	v_sub_f32_e32 v11, v11, v1
	v_sub_f32_e32 v28, v28, v1
	v_sub_f32_e32 v12, v12, v1
	v_sub_f32_e32 v29, v29, v1
	v_sub_f32_e32 v13, v13, v1
	v_sub_f32_e32 v30, v30, v1
	v_sub_f32_e32 v14, v14, v1
	v_sub_f32_e32 v31, v31, v1
	v_sub_f32_e32 v15, v15, v1
	v_sub_f32_e32 v32, v32, v1
	v_sub_f32_e32 v16, v16, v1
	v_sub_f32_e32 v33, v33, v1
	v_sub_f32_e32 v1, v17, v1
	s_nop 0
	v_exp_f32_e32 v66, v18
	v_exp_f32_e32 v81, v33
	v_exp_f32_e32 v67, v19
	v_exp_f32_e32 v68, v20
	v_exp_f32_e32 v69, v21
	v_exp_f32_e32 v70, v22
	v_exp_f32_e32 v71, v23
	v_exp_f32_e32 v72, v24
	v_exp_f32_e32 v73, v25
	v_exp_f32_e32 v74, v26
	v_exp_f32_e32 v75, v27
	v_exp_f32_e32 v76, v28
	v_exp_f32_e32 v77, v29
	v_exp_f32_e32 v78, v30
	v_exp_f32_e32 v79, v31
	v_exp_f32_e32 v80, v32
	v_exp_f32_e32 v65, v1
	v_exp_f32_e32 v50, v50
	v_exp_f32_e32 v51, v51
	v_exp_f32_e32 v52, v4
	v_exp_f32_e32 v53, v5
	v_exp_f32_e32 v54, v6
	v_exp_f32_e32 v55, v7
	v_exp_f32_e32 v56, v8
	v_exp_f32_e32 v57, v9
	v_exp_f32_e32 v58, v10
	v_exp_f32_e32 v59, v11
	v_exp_f32_e32 v60, v12
	v_exp_f32_e32 v61, v13
	v_exp_f32_e32 v62, v14
	v_exp_f32_e32 v63, v15
	v_exp_f32_e32 v64, v16
	s_waitcnt vmcnt(2) lgkmcnt(0)
	s_barrier
	v_mov_b32_e32 v2, v0
	v_mov_b32_e32 v3, v0
	v_mov_b32_e32 v4, v0
	v_mov_b32_e32 v5, v0
	v_mov_b32_e32 v6, v0
	v_mov_b32_e32 v7, v0
	v_mov_b32_e32 v8, v0
	v_mov_b32_e32 v9, v0
	v_mov_b32_e32 v10, v0
	v_mov_b32_e32 v11, v0
	v_mov_b32_e32 v12, v0
	v_mov_b32_e32 v13, v0
	v_mov_b32_e32 v14, v0
	v_mov_b32_e32 v15, v0
	v_mov_b32_e32 v16, v0
	v_mov_b32_e32 v17, v0
	v_mov_b32_e32 v18, v0
	v_mov_b32_e32 v19, v0
	v_mov_b32_e32 v20, v0
	v_mov_b32_e32 v21, v0
	v_mov_b32_e32 v22, v0
	v_mov_b32_e32 v23, v0
	v_mov_b32_e32 v24, v0
	v_mov_b32_e32 v25, v0
	v_mov_b32_e32 v26, v0
	v_mov_b32_e32 v27, v0
	v_mov_b32_e32 v28, v0
	v_mov_b32_e32 v29, v0
	v_mov_b32_e32 v30, v0
	v_mov_b32_e32 v31, v0
	v_mov_b32_e32 v1, v0
	v_mov_b64_e32 v[32:33], v[30:31]
	v_cmp_gt_u32_e64 s[4:5], 32, v203
	v_mov_b64_e32 v[30:31], v[28:29]
	v_mov_b64_e32 v[28:29], v[26:27]
	v_mov_b64_e32 v[26:27], v[24:25]
	v_mov_b64_e32 v[24:25], v[22:23]
	v_mov_b64_e32 v[22:23], v[20:21]
	v_mov_b64_e32 v[20:21], v[18:19]
	v_mov_b64_e32 v[18:19], v[16:17]
	v_mov_b64_e32 v[16:17], v[14:15]
	v_mov_b64_e32 v[14:15], v[12:13]
	v_mov_b64_e32 v[12:13], v[10:11]
	v_mov_b64_e32 v[10:11], v[8:9]
	v_mov_b64_e32 v[8:9], v[6:7]
	v_mov_b64_e32 v[6:7], v[4:5]
	v_mov_b64_e32 v[4:5], v[2:3]
	v_mov_b64_e32 v[2:3], v[0:1]
	v_readfirstlane_b32 s98, v182
	v_readfirstlane_b32 s99, v183
	s_mov_b64 s[100:101], 0
	s_nop 0
	v_subrev_u32_e32 v215, s98, v182
	v_subrev_u32_e32 v213, s98, v184
	v_add_u32_e32 v216, 0x48000, v215
	v_add_u32_e32 v214, 0x48000, v213
	s_add_u32 s98, s98, s62
	s_addc_u32 s99, s99, s63
	s_mov_b64 s[6:7], 0
.LBB0_383:
	v_add_u32_e32 v1, s20, v210
	ds_read_b64_tr_b16 v[178:179], v1 offset:24576
	ds_read_b64_tr_b16 v[180:181], v1 offset:25088
	s_waitcnt lgkmcnt(9)
	v_mfma_f32_32x32x16_bf16 v[98:113], v[174:177], v[130:133], v[34:49]
	v_add_f32_e32 v82, v66, v67
	v_add_f32_e32 v82, v68, v82
	v_add_f32_e32 v82, v69, v82
	v_add_f32_e32 v82, v70, v82
	v_add_f32_e32 v82, v71, v82
	v_cvt_pk_bf16_f32 v142, v66, v67
	v_cvt_pk_bf16_f32 v143, v68, v69
	ds_read_b64_tr_b16 v[174:175], v1 offset:28672
	ds_read_b64_tr_b16 v[176:177], v1 offset:29184
	v_add_f32_e32 v66, v72, v82
	s_waitcnt lgkmcnt(10)
	v_mfma_f32_32x32x16_bf16 v[82:97], v[170:173], v[130:133], v[34:49]
	v_add_f32_e32 v66, v73, v66
	v_add_f32_e32 v66, v74, v66
	v_add_f32_e32 v114, v75, v66
	v_cvt_pk_bf16_f32 v144, v70, v71
	v_cvt_pk_bf16_f32 v145, v72, v73
	ds_read_b64_tr_b16 v[66:67], v1 offset:25600
	ds_read_b64_tr_b16 v[68:69], v1 offset:26112
	s_waitcnt lgkmcnt(11)
	v_mfma_f32_32x32x16_bf16 v[98:113], v[166:169], v[122:125], v[98:113]
	v_add_f32_e32 v70, v76, v114
	v_add_f32_e32 v70, v77, v70
	v_add_f32_e32 v70, v78, v70
	v_add_f32_e32 v114, v79, v70
	v_cvt_pk_bf16_f32 v126, v74, v75
	v_cvt_pk_bf16_f32 v127, v76, v77
	ds_read_b64_tr_b16 v[70:71], v1 offset:29696
	ds_read_b64_tr_b16 v[72:73], v1 offset:30208
	s_waitcnt lgkmcnt(12)
	v_mfma_f32_32x32x16_bf16 v[82:97], v[162:165], v[122:125], v[82:97]
	v_add_f32_e32 v74, v80, v114
	v_add_f32_e32 v74, v81, v74
	v_add_f32_e32 v74, v50, v74
	v_add_f32_e32 v114, v51, v74
	v_cvt_pk_bf16_f32 v128, v78, v79
	v_cvt_pk_bf16_f32 v129, v80, v81
	ds_read_b64_tr_b16 v[74:75], v1 offset:26624
	ds_read_b64_tr_b16 v[76:77], v1 offset:27136
	s_waitcnt lgkmcnt(13)
	v_mfma_f32_32x32x16_bf16 v[98:113], v[158:161], v[138:141], v[98:113]
	v_add_f32_e32 v78, v52, v114
	v_add_f32_e32 v78, v53, v78
	v_add_f32_e32 v78, v54, v78
	v_add_f32_e32 v78, v55, v78
	v_cvt_pk_bf16_f32 v118, v50, v51
	v_cvt_pk_bf16_f32 v119, v52, v53
	ds_read_b64_tr_b16 v[50:51], v1 offset:30720
	ds_read_b64_tr_b16 v[52:53], v1 offset:31232
	s_waitcnt lgkmcnt(14)
	v_mfma_f32_32x32x16_bf16 v[82:97], v[154:157], v[138:141], v[82:97]
	v_add_f32_e32 v78, v56, v78
	v_add_f32_e32 v78, v57, v78
	v_add_f32_e32 v78, v58, v78
	v_add_f32_e32 v78, v59, v78
	v_cvt_pk_bf16_f32 v120, v54, v55
	v_cvt_pk_bf16_f32 v121, v56, v57
	ds_read_b64_tr_b16 v[54:55], v1 offset:27648
	ds_read_b64_tr_b16 v[56:57], v1 offset:28160
	s_waitcnt lgkmcnt(14)
	v_mfma_f32_32x32x16_bf16 v[98:113], v[150:153], v[134:137], v[98:113]
	v_add_f32_e32 v78, v60, v78
	v_add_f32_e32 v78, v61, v78
	v_add_f32_e32 v78, v62, v78
	v_add_f32_e32 v78, v63, v78
	v_cvt_pk_bf16_f32 v114, v58, v59
	v_cvt_pk_bf16_f32 v115, v60, v61
	ds_read_b64_tr_b16 v[58:59], v1 offset:31744
	ds_read_b64_tr_b16 v[60:61], v1 offset:32256
	v_mfma_f32_32x32x16_bf16 v[82:97], v[146:149], v[134:137], v[82:97]
	v_add_f32_e32 v1, v64, v78
	v_add_f32_e32 v1, v65, v1
	v_cvt_pk_bf16_f32 v116, v62, v63
	v_cvt_pk_bf16_f32 v117, v64, v65
	s_add_i32 s2, s3, s22
	s_mov_b32 m0, s2
	s_nop 0
	global_load_lds_dwordx4 v213, s[98:99]
	s_add_i32 s2, s27, s23
	s_mov_b32 m0, s2
	s_nop 0
	global_load_lds_dwordx4 v215, s[98:99]
	v_max_f32_e32 v62, v98, v99
	v_max3_f32 v63, v100, v101, v83
	v_max3_f32 v62, v62, v82, v84
	v_max3_f32 v62, v62, v85, v102
	v_max3_f32 v63, v63, v104, v105
	v_max3_f32 v62, v62, v103, v86
	v_max3_f32 v63, v63, v88, v89
	v_max3_f32 v62, v62, v87, v106
	v_max3_f32 v63, v63, v108, v109
	v_max3_f32 v62, v62, v107, v90
	v_max3_f32 v63, v63, v92, v93
	v_max3_f32 v62, v62, v91, v110
	v_max3_f32 v63, v63, v112, v113
	v_max3_f32 v62, v62, v111, v94
	v_max3_f32 v63, v63, v96, v97
	v_max3_f32 v62, v62, v95, v63
	v_cmp_lt_f32_e32 vcc, s19, v62
	v_add_f32_e32 v1, v212, v1
	s_cbranch_vccnz .LBB0_391
.LBB0_384:
	s_waitcnt lgkmcnt(14)
	v_mfma_f32_32x32x16_bf16 v[2:17], v[142:145], v[178:181], v[2:17]
	v_exp_f32_e32 v98, v98
	v_exp_f32_e32 v99, v99
	v_exp_f32_e32 v100, v100
	v_exp_f32_e32 v101, v101
	s_waitcnt lgkmcnt(12)
	v_mfma_f32_32x32x16_bf16 v[18:33], v[142:145], v[174:177], v[18:33]
	v_exp_f32_e32 v102, v102
	v_exp_f32_e32 v103, v103
	v_exp_f32_e32 v104, v104
	v_exp_f32_e32 v105, v105
	v_add_u32_e32 v78, s27, v211
	ds_read_b128 v[62:65], v78
	ds_read_b128 v[174:177], v78 offset:512
	s_waitcnt lgkmcnt(12)
	v_mfma_f32_32x32x16_bf16 v[2:17], v[126:129], v[66:69], v[2:17]
	v_exp_f32_e32 v106, v106
	v_exp_f32_e32 v107, v107
	v_exp_f32_e32 v108, v108
	v_exp_f32_e32 v109, v109
	ds_read_b128 v[178:181], v78 offset:2048
	ds_read_b128 v[170:173], v78 offset:2560
	s_waitcnt lgkmcnt(12)
	v_mfma_f32_32x32x16_bf16 v[18:33], v[126:129], v[70:73], v[18:33]
	v_exp_f32_e32 v110, v110
	v_exp_f32_e32 v111, v111
	v_exp_f32_e32 v112, v112
	v_exp_f32_e32 v113, v113
	ds_read_b128 v[166:169], v78 offset:4096
	ds_read_b128 v[162:165], v78 offset:4608
	s_waitcnt lgkmcnt(12)
	v_mfma_f32_32x32x16_bf16 v[2:17], v[118:121], v[74:77], v[2:17]
	v_exp_f32_e32 v82, v82
	v_exp_f32_e32 v83, v83
	v_exp_f32_e32 v84, v84
	v_exp_f32_e32 v85, v85
	ds_read_b128 v[158:161], v78 offset:6144
	ds_read_b128 v[154:157], v78 offset:6656
	s_waitcnt lgkmcnt(12)
	v_mfma_f32_32x32x16_bf16 v[18:33], v[118:121], v[50:53], v[18:33]
	v_exp_f32_e32 v86, v86
	v_exp_f32_e32 v87, v87
	v_exp_f32_e32 v88, v88
	v_exp_f32_e32 v89, v89
	s_waitcnt lgkmcnt(10)
	v_mfma_f32_32x32x16_bf16 v[2:17], v[114:117], v[54:57], v[2:17]
	v_exp_f32_e32 v90, v90
	v_exp_f32_e32 v91, v91
	v_exp_f32_e32 v92, v92
	v_exp_f32_e32 v93, v93
	s_waitcnt lgkmcnt(8)
	v_mfma_f32_32x32x16_bf16 v[18:33], v[114:117], v[58:61], v[18:33]
	v_exp_f32_e32 v94, v94
	v_exp_f32_e32 v95, v95
	v_exp_f32_e32 v96, v96
	v_exp_f32_e32 v97, v97
	s_add_i32 s2, s27, 0x2000
	s_cmpk_lg_i32 s27, 0x4000
	s_cselect_b32 s14, s2, 0
	s_cmp_lg_u32 s6, 0
	s_waitcnt vmcnt(2) lgkmcnt(0)
	s_barrier
	s_cbranch_scc0 .LBB0_386
	s_waitcnt lgkmcnt(0)
	v_add_u32_e32 v66, s25, v193
	ds_read_b128 v[50:53], v66 offset:96
	ds_read_b128 v[54:57], v66 offset:64
	ds_read_b128 v[58:61], v66 offset:32
	ds_read_b128 v[66:69], v66
	s_waitcnt lgkmcnt(3)
	v_pk_mul_f32 v[14:15], v[14:15], v[50:51]
	s_waitcnt lgkmcnt(2)
	v_pk_mul_f32 v[10:11], v[10:11], v[54:55]
	s_waitcnt lgkmcnt(1)
	v_pk_mul_f32 v[6:7], v[6:7], v[58:59]
	v_pk_mul_f32 v[16:17], v[16:17], v[52:53]
	v_pk_mul_f32 v[12:13], v[12:13], v[56:57]
	v_pk_mul_f32 v[8:9], v[8:9], v[60:61]
	s_waitcnt lgkmcnt(0)
	v_pk_mul_f32 v[4:5], v[4:5], v[68:69]
	v_pk_mul_f32 v[2:3], v[2:3], v[66:67]
	v_pk_mul_f32 v[30:31], v[30:31], v[50:51]
	v_pk_mul_f32 v[26:27], v[26:27], v[54:55]
	v_pk_mul_f32 v[22:23], v[22:23], v[58:59]
	v_pk_mul_f32 v[32:33], v[32:33], v[52:53]
	v_pk_mul_f32 v[28:29], v[28:29], v[56:57]
	v_pk_mul_f32 v[24:25], v[24:25], v[60:61]
	v_pk_mul_f32 v[20:21], v[20:21], v[68:69]
	v_pk_mul_f32 v[18:19], v[18:19], v[66:67]
	s_mov_b64 s[6:7], 0
.LBB0_386:
	v_add_u32_e32 v186, s3, v210
	ds_read_b64_tr_b16 v[150:151], v186 offset:24576
	ds_read_b64_tr_b16 v[152:153], v186 offset:25088
	s_waitcnt lgkmcnt(9)
	v_mfma_f32_32x32x16_bf16 v[66:81], v[62:65], v[130:133], v[34:49]
	v_add_f32_e32 v50, v98, v99
	v_add_f32_e32 v50, v100, v50
	v_add_f32_e32 v50, v101, v50
	v_add_f32_e32 v50, v102, v50
	v_add_f32_e32 v50, v103, v50
	v_cvt_pk_bf16_f32 v142, v98, v99
	v_cvt_pk_bf16_f32 v143, v100, v101
	ds_read_b64_tr_b16 v[146:147], v186 offset:28672
	ds_read_b64_tr_b16 v[148:149], v186 offset:29184
	v_add_f32_e32 v50, v104, v50
	v_add_f32_e32 v50, v105, v50
	v_add_f32_e32 v50, v106, v50
	v_add_f32_e32 v114, v107, v50
	s_waitcnt lgkmcnt(10)
	v_mfma_f32_32x32x16_bf16 v[50:65], v[174:177], v[130:133], v[34:49]
	v_cvt_pk_bf16_f32 v144, v102, v103
	v_cvt_pk_bf16_f32 v145, v104, v105
	ds_read_b64_tr_b16 v[98:99], v186 offset:25600
	ds_read_b64_tr_b16 v[100:101], v186 offset:26112
	s_waitcnt lgkmcnt(11)
	v_mfma_f32_32x32x16_bf16 v[66:81], v[178:181], v[122:125], v[66:81]
	v_add_f32_e32 v102, v108, v114
	v_add_f32_e32 v102, v109, v102
	v_add_f32_e32 v102, v110, v102
	v_add_f32_e32 v114, v111, v102
	v_cvt_pk_bf16_f32 v126, v106, v107
	v_cvt_pk_bf16_f32 v127, v108, v109
	ds_read_b64_tr_b16 v[102:103], v186 offset:29696
	ds_read_b64_tr_b16 v[104:105], v186 offset:30208
	s_waitcnt lgkmcnt(12)
	v_mfma_f32_32x32x16_bf16 v[50:65], v[170:173], v[122:125], v[50:65]
	v_add_f32_e32 v106, v112, v114
	v_add_f32_e32 v106, v113, v106
	v_add_f32_e32 v106, v82, v106
	v_add_f32_e32 v114, v83, v106
	v_cvt_pk_bf16_f32 v128, v110, v111
	v_cvt_pk_bf16_f32 v129, v112, v113
	ds_read_b64_tr_b16 v[106:107], v186 offset:26624
	ds_read_b64_tr_b16 v[108:109], v186 offset:27136
	s_waitcnt lgkmcnt(13)
	v_mfma_f32_32x32x16_bf16 v[66:81], v[166:169], v[138:141], v[66:81]
	v_add_f32_e32 v110, v84, v114
	v_add_f32_e32 v110, v85, v110
	v_add_f32_e32 v110, v86, v110
	v_add_f32_e32 v110, v87, v110
	v_cvt_pk_bf16_f32 v118, v82, v83
	v_cvt_pk_bf16_f32 v119, v84, v85
	ds_read_b64_tr_b16 v[82:83], v186 offset:30720
	ds_read_b64_tr_b16 v[84:85], v186 offset:31232
	s_waitcnt lgkmcnt(14)
	v_mfma_f32_32x32x16_bf16 v[50:65], v[162:165], v[138:141], v[50:65]
	v_add_f32_e32 v110, v88, v110
	v_add_f32_e32 v110, v89, v110
	v_add_f32_e32 v110, v90, v110
	v_add_f32_e32 v110, v91, v110
	v_cvt_pk_bf16_f32 v120, v86, v87
	v_cvt_pk_bf16_f32 v121, v88, v89
	ds_read_b64_tr_b16 v[86:87], v186 offset:27648
	ds_read_b64_tr_b16 v[88:89], v186 offset:28160
	s_waitcnt lgkmcnt(14)
	v_mfma_f32_32x32x16_bf16 v[66:81], v[158:161], v[134:137], v[66:81]
	v_add_f32_e32 v110, v92, v110
	v_add_f32_e32 v110, v93, v110
	v_add_f32_e32 v110, v94, v110
	v_add_f32_e32 v110, v95, v110
	v_cvt_pk_bf16_f32 v114, v90, v91
	v_cvt_pk_bf16_f32 v115, v92, v93
	ds_read_b64_tr_b16 v[90:91], v186 offset:31744
	ds_read_b64_tr_b16 v[92:93], v186 offset:32256
	v_mfma_f32_32x32x16_bf16 v[50:65], v[154:157], v[134:137], v[50:65]
	v_add_f32_e32 v110, v96, v110
	v_add_f32_e32 v110, v97, v110
	v_cvt_pk_bf16_f32 v116, v94, v95
	v_cvt_pk_bf16_f32 v117, v96, v97
	v_max_f32_e32 v94, v66, v67
	v_max3_f32 v95, v68, v69, v70
	v_max3_f32 v94, v94, v71, v72
	v_max3_f32 v95, v95, v73, v74
	v_max3_f32 v94, v94, v75, v76
	v_max3_f32 v95, v95, v77, v78
	v_max3_f32 v94, v94, v79, v80
	v_add_f32_e32 v212, v1, v110
	v_max3_f32 v95, v95, v81, v50
	v_max3_f32 v94, v94, v51, v52
	v_max3_f32 v95, v95, v53, v54
	v_max3_f32 v94, v94, v55, v56
	v_max3_f32 v95, v95, v57, v58
	v_max3_f32 v94, v94, v59, v60
	v_max3_f32 v95, v95, v61, v62
	v_max3_f32 v94, v94, v63, v64
	v_max3_f32 v1, v94, v65, v95
	s_add_i32 s2, s27, s22
	s_mov_b32 m0, s2
	s_nop 0
	global_load_lds_dwordx4 v214, s[98:99]
	s_add_i32 s2, s14, s23
	s_mov_b32 m0, s2
	s_nop 0
	global_load_lds_dwordx4 v216, s[98:99]
	v_cmp_lt_f32_e32 vcc, s19, v1
	s_cbranch_vccnz .LBB0_394

;   #define WAIT_KV() do{ if constexpr(DV==128){WAIT_BAR(3);} else {WAIT_BAR(2);} }while(0)
;   #define RESC() do{ if(resc){ asm volatile("s_waitcnt lgkmcnt(0)":::"memory"); \
;       _Pragma("unroll") for(int d_=0;d_<DV/32;++d_) _Pragma("unroll") for(int r=0;r<16;++r)o[d_][r]*=wsf[crow(r,hi)]; } }while(0)
;   #define ROT() do{sl_prev=sl_cur;sl_cur=sl_next;sl_next=(sl_next==(NSLOT-1)*SLOTB)?0:sl_next+SLOTB;}while(0)
; template<int THRL,bool WIN,int DM,int ODM,int DV,int QMODE> __device__ __forceinline__ void attn_unit(const bf16*Qp,const bf16*__restrict__ Kp,const bf16*__restrict__ Vp,bf16*Op,const int q0,const int t_lo,const int NT,const float sink2,char*shm,const float*qgain,const float*qtab,const int b0,const ...
;     ...
;   f32x16 pA0,pA1,pB0,pB1;
;   int sl_prev=s0,sl_cur=s0,sl_next=s1;
;     ...
;   for(;t+5<NT;t+=2){
;     STEP(pB0,pB1,pA0,pA1,t,true,true,true);     WAIT_KV(); RESC(); ROT();
;     STEP(pA0,pA1,pB0,pB1,t+1,true,true,true);   WAIT_KV(); RESC(); ROT();
;   }
.LBB0_389:
	s_add_i32 s13, s13, 2
	s_add_i32 s2, s14, 0x2000
	s_cmpk_lg_i32 s14, 0x4000
	s_cselect_b32 s2, s2, 0
	s_add_i32 s3, s26, 2
	s_add_u32 s98, s98, 0x90000
	s_addc_u32 s99, s99, 0
	s_add_u32 s100, s100, 0x90000
	s_addc_u32 s101, s101, 0
	s_cmp_ge_u32 s13, s15
	s_cbranch_scc1 .Lmy_a_exitbar
	s_mov_b32 s26, s3
	s_mov_b32 s20, s27
	s_mov_b32 s3, s14
	s_mov_b32 s27, s2
	s_cmp_lg_u32 s6, 0
	s_waitcnt vmcnt(2) lgkmcnt(0)
	s_barrier
	s_cbranch_scc0 .LBB0_383
	s_waitcnt lgkmcnt(0)
	v_add_u32_e32 v1, s25, v193
	ds_read_b128 v[82:85], v1 offset:96
	ds_read_b128 v[86:89], v1 offset:64
	ds_read_b128 v[90:93], v1 offset:32
	ds_read_b128 v[94:97], v1
	s_waitcnt lgkmcnt(3)
	v_pk_mul_f32 v[14:15], v[14:15], v[82:83]
	s_waitcnt lgkmcnt(2)
	v_pk_mul_f32 v[10:11], v[10:11], v[86:87]
	s_waitcnt lgkmcnt(1)
	v_pk_mul_f32 v[6:7], v[6:7], v[90:91]
	v_pk_mul_f32 v[16:17], v[16:17], v[84:85]
	v_pk_mul_f32 v[12:13], v[12:13], v[88:89]
	v_pk_mul_f32 v[8:9], v[8:9], v[92:93]
	s_waitcnt lgkmcnt(0)
	v_pk_mul_f32 v[4:5], v[4:5], v[96:97]
	v_pk_mul_f32 v[2:3], v[2:3], v[94:95]
	v_pk_mul_f32 v[30:31], v[30:31], v[82:83]
	v_pk_mul_f32 v[26:27], v[26:27], v[86:87]
	v_pk_mul_f32 v[22:23], v[22:23], v[90:91]
	v_pk_mul_f32 v[32:33], v[32:33], v[84:85]
	v_pk_mul_f32 v[28:29], v[28:29], v[88:89]
	v_pk_mul_f32 v[24:25], v[24:25], v[92:93]
	v_pk_mul_f32 v[20:21], v[20:21], v[96:97]
	v_pk_mul_f32 v[18:19], v[18:19], v[94:95]
	s_mov_b64 s[6:7], 0
	s_branch .LBB0_383
.Lmy_a_exitbar:
	s_cmp_lg_u32 s6, 0
	s_waitcnt vmcnt(2) lgkmcnt(0)
	s_barrier
	s_cbranch_scc0 .Lmy_a_exit
	s_waitcnt lgkmcnt(0)
	v_add_u32_e32 v1, s25, v193
	ds_read_b128 v[82:85], v1 offset:96
	ds_read_b128 v[86:89], v1 offset:64
	ds_read_b128 v[90:93], v1 offset:32
	ds_read_b128 v[94:97], v1
	s_waitcnt lgkmcnt(3)
	v_pk_mul_f32 v[14:15], v[14:15], v[82:83]
	s_waitcnt lgkmcnt(2)
	v_pk_mul_f32 v[10:11], v[10:11], v[86:87]
	s_waitcnt lgkmcnt(1)
	v_pk_mul_f32 v[6:7], v[6:7], v[90:91]
	v_pk_mul_f32 v[16:17], v[16:17], v[84:85]
	v_pk_mul_f32 v[12:13], v[12:13], v[88:89]
	v_pk_mul_f32 v[8:9], v[8:9], v[92:93]
	s_waitcnt lgkmcnt(0)
	v_pk_mul_f32 v[4:5], v[4:5], v[96:97]
	v_pk_mul_f32 v[2:3], v[2:3], v[94:95]
	v_pk_mul_f32 v[30:31], v[30:31], v[82:83]
	v_pk_mul_f32 v[26:27], v[26:27], v[86:87]
	v_pk_mul_f32 v[22:23], v[22:23], v[90:91]
	v_pk_mul_f32 v[32:33], v[32:33], v[84:85]
	v_pk_mul_f32 v[28:29], v[28:29], v[88:89]
	v_pk_mul_f32 v[24:25], v[24:25], v[92:93]
	v_pk_mul_f32 v[20:21], v[20:21], v[96:97]
	v_pk_mul_f32 v[18:19], v[18:19], v[94:95]
	s_mov_b64 s[6:7], 0

.LBB0_391:
	s_mov_b64 s[6:7], -1
	v_mov_b32_e32 v63, v62
	s_nop 1
	v_permlane32_swap_b32_e32 v62, v63
	v_max_f32_e32 v62, v62, v63
	v_max_f32_e32 v34, v62, v62
	v_max_f32_e32 v62, 0, v34
	v_exp_f32_e64 v63, -v62
	v_add_f32_e32 v209, v209, v62
	v_xor_b32_e32 v34, 0x80000000, v209
	v_mov_b32_e32 v35, v34
	v_mov_b32_e32 v36, v34
	v_mov_b32_e32 v37, v34
	v_mov_b32_e32 v38, v34
	v_mov_b32_e32 v39, v34
	v_mov_b32_e32 v40, v34
	v_mov_b32_e32 v41, v34
	v_mov_b32_e32 v42, v34
	v_mov_b32_e32 v43, v34
	v_mov_b32_e32 v44, v34
	v_mov_b32_e32 v45, v34
	v_mov_b32_e32 v46, v34
	v_mov_b32_e32 v47, v34
	v_mov_b32_e32 v48, v34
	v_mov_b32_e32 v49, v34
	s_and_saveexec_b64 s[20:21], s[4:5]
	ds_write_b32 v208, v63
	s_or_b64 exec, exec, s[20:21]
	v_sub_f32_e32 v113, v113, v62
	v_sub_f32_e32 v112, v112, v62
	v_sub_f32_e32 v111, v111, v62
	v_sub_f32_e32 v110, v110, v62
	v_sub_f32_e32 v109, v109, v62
	v_sub_f32_e32 v108, v108, v62
	v_sub_f32_e32 v107, v107, v62
	v_sub_f32_e32 v106, v106, v62
	v_sub_f32_e32 v105, v105, v62
	v_sub_f32_e32 v104, v104, v62
	v_sub_f32_e32 v103, v103, v62
	v_sub_f32_e32 v102, v102, v62
	v_sub_f32_e32 v101, v101, v62
	v_sub_f32_e32 v100, v100, v62
	v_sub_f32_e32 v99, v99, v62
	v_sub_f32_e32 v98, v98, v62
	v_sub_f32_e32 v97, v97, v62
	v_sub_f32_e32 v96, v96, v62
	v_sub_f32_e32 v95, v95, v62
	v_sub_f32_e32 v94, v94, v62
	v_sub_f32_e32 v93, v93, v62
	v_sub_f32_e32 v92, v92, v62
	v_sub_f32_e32 v91, v91, v62
	v_sub_f32_e32 v90, v90, v62
	v_sub_f32_e32 v89, v89, v62
	v_sub_f32_e32 v88, v88, v62
	v_sub_f32_e32 v87, v87, v62
	v_sub_f32_e32 v86, v86, v62
	v_sub_f32_e32 v85, v85, v62
	v_sub_f32_e32 v84, v84, v62
	v_sub_f32_e32 v83, v83, v62
	v_sub_f32_e32 v82, v82, v62
	v_mul_f32_e32 v1, v1, v63
	s_branch .LBB0_384
.LBB0_394:
	s_mov_b64 s[6:7], -1
	v_mov_b32_e32 v94, v1
	s_nop 1
	v_permlane32_swap_b32_e32 v1, v94
	v_max_f32_e32 v1, v1, v94
	v_max_f32_e32 v1, v1, v1
	v_max_f32_e32 v1, 0, v1
	v_exp_f32_e64 v94, -v1
	v_add_f32_e32 v209, v209, v1
	v_xor_b32_e32 v34, 0x80000000, v209
	v_mov_b32_e32 v35, v34
	v_mov_b32_e32 v36, v34
	v_mov_b32_e32 v37, v34
	v_mov_b32_e32 v38, v34
	v_mov_b32_e32 v39, v34
	v_mov_b32_e32 v40, v34
	v_mov_b32_e32 v41, v34
	v_mov_b32_e32 v42, v34
	v_mov_b32_e32 v43, v34
	v_mov_b32_e32 v44, v34
	v_mov_b32_e32 v45, v34
	v_mov_b32_e32 v46, v34
	v_mov_b32_e32 v47, v34
	v_mov_b32_e32 v48, v34
	v_mov_b32_e32 v49, v34
	s_and_saveexec_b64 s[20:21], s[4:5]
	ds_write_b32 v208, v94
	s_or_b64 exec, exec, s[20:21]
	v_sub_f32_e32 v81, v81, v1
	v_sub_f32_e32 v80, v80, v1
	v_sub_f32_e32 v79, v79, v1
	v_sub_f32_e32 v78, v78, v1
	v_sub_f32_e32 v77, v77, v1
	v_sub_f32_e32 v76, v76, v1
	v_sub_f32_e32 v75, v75, v1
	v_sub_f32_e32 v74, v74, v1
	v_sub_f32_e32 v73, v73, v1
	v_sub_f32_e32 v72, v72, v1
	v_sub_f32_e32 v71, v71, v1
	v_sub_f32_e32 v70, v70, v1
	v_sub_f32_e32 v69, v69, v1
	v_sub_f32_e32 v68, v68, v1
	v_sub_f32_e32 v67, v67, v1
	v_sub_f32_e32 v66, v66, v1
	v_sub_f32_e32 v65, v65, v1
	v_sub_f32_e32 v64, v64, v1
	v_sub_f32_e32 v63, v63, v1
	v_sub_f32_e32 v62, v62, v1
	v_sub_f32_e32 v61, v61, v1
	v_sub_f32_e32 v60, v60, v1
	v_sub_f32_e32 v59, v59, v1
	v_sub_f32_e32 v58, v58, v1
	v_sub_f32_e32 v57, v57, v1
	v_sub_f32_e32 v56, v56, v1
	v_sub_f32_e32 v55, v55, v1
	v_sub_f32_e32 v54, v54, v1
	v_sub_f32_e32 v53, v53, v1
	v_sub_f32_e32 v52, v52, v1
	v_sub_f32_e32 v51, v51, v1
	v_sub_f32_e32 v50, v50, v1
	v_mul_f32_e32 v212, v212, v94
	s_branch .LBB0_387

; __device__ __forceinline__ unsigned cvtpk_s(float lo,float hi){f32x2_t v={lo,hi};bf16x2_t b=__builtin_convertvector(v,bf16x2_t);return __builtin_bit_cast(unsigned,b);}
; #define WAIT_BAR(N) asm volatile("s_waitcnt vmcnt(" #N ") lgkmcnt(0)\n\ts_barrier":::"memory")
;   #define CMASK(P0,P1,t) do{ if constexpr(WIN){ wmask(P0,P1,(t_lo+(t))*KVBLK+4*hi,qpos); } }while(0)
; template<int THRL,bool WIN,int DM,int ODM,int DV,int QMODE> __device__ __forceinline__ void attn_unit(const bf16*Qp,const bf16*__restrict__ Kp,const bf16*__restrict__ Vp,bf16*Op,const int q0,const int t_lo,const int NT,const float sink2,char*shm,const float*qgain,const float*qtab,const int b0,const ...
;     ...
;       const float*tb=qtab+(size_t)qpos*16;
;       const f32x4_t c0=*(const f32x4_t*)(tb),c1=*(const f32x4_t*)(tb+4),c2=*(const f32x4_t*)(tb+8),c3=*(const f32x4_t*)(tb+12);
;       const float cc[8]={c0.x,c0.z,c1.x,c1.z,c2.x,c2.z,c3.x,c3.z},sn[8]={c0.y,c0.w,c1.y,c1.w,c2.y,c2.w,c3.y,c3.w};
;       const float sg=hi?1.f:-1.f;
;       #pragma unroll
;       for(int e=0;e<8;++e){ const float p=__builtin_bit_cast(float,__builtin_amdgcn_ds_bpermute(bp,__builtin_bit_cast(int,v[0][e]))); v[0][e]=v[0][e]*cc[e]+sg*(p*sn[e]); }
;     }
;     #pragma unroll
;     for(int d0=0;d0<4;++d0){ u32x4 w; w[0]=cvtpk_s(v[d0][0]*QS,v[d0][1]*QS); w[1]=cvtpk_s(v[d0][2]*QS,v[d0][3]*QS); w[2]=cvtpk_s(v[d0][4]*QS,v[d0][5]*QS); w[3]=cvtpk_s(v[d0][6]*QS,v[d0][7]*QS);
;       qr[d0]=__builtin_bit_cast(bf16x8,w); }
;   }
;   WAIT_BAR(3);
;   qkt(pA0,pA1,Kbase+s0,qr,negm,r32,hi);asm volatile("s_nop 15\n\ts_nop 7":"+v"(pA0),"+v"(pA1));CMASK(pA0,pA1,0);
.LBB0_464:
	v_or_b32_e32 v36, s38, v244
	v_add_u32_e32 v36, s84, v36
	v_ashrrev_i32_e32 v37, 31, v36
	v_lshlrev_b64 v[36:37], 6, v[36:37]
	v_lshl_add_u64 v[36:37], s[8:9], 0, v[36:37]
	global_load_dwordx4 v[40:43], v[36:37], off
	global_load_dwordx4 v[44:47], v[36:37], off offset:16
	global_load_dwordx4 v[64:67], v[36:37], off offset:32
	global_load_dwordx4 v[68:71], v[36:37], off offset:48
	v_lshlrev_b32_e32 v74, 2, v253
	s_waitcnt vmcnt(7)
	v_and_b32_e32 v37, 0xffff0000, v32
	v_lshlrev_b32_e32 v36, 16, v32
	v_and_b32_e32 v39, 0xffff0000, v33
	v_lshlrev_b32_e32 v38, 16, v33
	v_and_b32_e32 v33, 0xffff0000, v34
	v_lshlrev_b32_e32 v32, 16, v34
	v_and_b32_e32 v81, 0xffff0000, v35
	v_lshlrev_b32_e32 v80, 16, v35
	s_waitcnt vmcnt(6)
	v_and_b32_e32 v35, 0xffff0000, v56
	v_lshlrev_b32_e32 v34, 16, v56
	v_and_b32_e32 v73, 0xffff0000, v57
	v_lshlrev_b32_e32 v72, 16, v57
	v_and_b32_e32 v57, 0xffff0000, v58
	v_lshlrev_b32_e32 v56, 16, v58
	v_xor_b32_e32 v58, 0x80, v74
	ds_bpermute_b32 v84, v58, v36
	ds_bpermute_b32 v85, v58, v37
	ds_bpermute_b32 v86, v58, v38
	ds_bpermute_b32 v87, v58, v39
	ds_bpermute_b32 v88, v58, v32
	ds_bpermute_b32 v89, v58, v33
	ds_bpermute_b32 v90, v58, v80
	ds_bpermute_b32 v91, v58, v81
	v_lshlrev_b32_e32 v92, 10, v251
	v_lshlrev_b32_e32 v93, 4, v244
	s_add_i32 s4, s15, 0
	v_pk_mul_f32 v[34:35], v[34:35], s[50:51] op_sel_hi:[1,0]
	v_pk_mul_f32 v[56:57], v[56:57], s[50:51] op_sel_hi:[1,0]
	v_pk_mul_f32 v[72:73], v[72:73], s[50:51] op_sel_hi:[1,0]
	v_add3_u32 v94, s4, v92, v93
	v_cvt_pk_bf16_f32 v162, v34, v35
	v_cvt_pk_bf16_f32 v164, v56, v57
	s_waitcnt vmcnt(3) lgkmcnt(0)
	s_barrier
	v_cvt_pk_bf16_f32 v163, v72, v73
	ds_read_b128 v[72:75], v94 offset:512
	ds_read_b128 v[76:79], v94
	v_cmp_gt_u32_e64 s[4:5], 32, v253
	v_and_b32_e32 v83, 0xffff0000, v59
	v_lshlrev_b32_e32 v82, 16, v59
	v_lshlrev_b32_e32 v63, 1, v62
	v_and_b32_e32 v223, 32, v63
	s_and_b32 s2, s2, 0x3fffffc0
	s_lshl_b32 s2, s2, 2
	s_add_i32 s65, s2, 0
	s_add_i32 s2, s47, s15
	v_add3_u32 v214, 0, v92, v93
	s_add_i32 s65, s65, 0x12000
	s_xor_b64 s[82:83], s[86:87], -1
	s_mov_b32 s13, 1
	v_lshl_add_u32 v242, v244, 2, s65
	v_lshlrev_b32_e32 v243, 4, v251
	v_lshl_add_u64 v[230:231], v[226:227], 0, s[60:61]
	v_mov_b32_e32 v215, 0
	s_mov_b32 s96, 5
	s_waitcnt vmcnt(3)
	v_mov_b32_e32 v35, v42
	v_mov_b32_e32 v42, v41
	s_waitcnt vmcnt(2)
	v_mov_b32_e32 v41, v46
	v_mov_b32_e32 v46, v45
	s_waitcnt vmcnt(1)
	v_mov_b32_e32 v45, v66
	v_mov_b32_e32 v66, v65
	s_waitcnt vmcnt(0)
	v_mov_b32_e32 v57, v70
	v_mov_b32_e32 v70, v69
	v_mov_b32_e32 v34, v40
	v_mov_b32_e32 v40, v44
	v_mov_b32_e32 v44, v64
	s_waitcnt lgkmcnt(8)
	v_pk_mul_f32 v[42:43], v[42:43], v[84:85]
	s_waitcnt lgkmcnt(6)
	v_pk_mul_f32 v[46:47], v[46:47], v[86:87]
	s_waitcnt lgkmcnt(4)
	v_pk_mul_f32 v[64:65], v[66:67], v[88:89]
	s_waitcnt lgkmcnt(2)
	v_pk_mul_f32 v[66:67], v[70:71], v[90:91]
	v_mov_b32_e32 v56, v68
	v_cndmask_b32_e64 v43, v43, -v43, s[4:5]
	v_cndmask_b32_e64 v42, v42, -v42, s[4:5]
	v_cndmask_b32_e64 v47, v47, -v47, s[4:5]
	v_cndmask_b32_e64 v46, v46, -v46, s[4:5]
	v_cndmask_b32_e64 v65, v65, -v65, s[4:5]
	v_cndmask_b32_e64 v64, v64, -v64, s[4:5]
	v_cndmask_b32_e64 v67, v67, -v67, s[4:5]
	v_cndmask_b32_e64 v66, v66, -v66, s[4:5]
	v_pk_fma_f32 v[34:35], v[34:35], v[36:37], v[42:43]
	v_pk_fma_f32 v[36:37], v[40:41], v[38:39], v[46:47]
	v_pk_fma_f32 v[32:33], v[44:45], v[32:33], v[64:65]
	v_pk_fma_f32 v[38:39], v[56:57], v[80:81], v[66:67]
	v_pk_mul_f32 v[34:35], v[34:35], s[50:51] op_sel_hi:[1,0]
	v_pk_mul_f32 v[36:37], v[36:37], s[50:51] op_sel_hi:[1,0]
	v_pk_mul_f32 v[32:33], v[32:33], s[50:51] op_sel_hi:[1,0]
	v_pk_mul_f32 v[38:39], v[38:39], s[50:51] op_sel_hi:[1,0]
	v_cvt_pk_bf16_f32 v174, v34, v35
	v_cvt_pk_bf16_f32 v175, v36, v37
	v_cvt_pk_bf16_f32 v176, v32, v33
	v_cvt_pk_bf16_f32 v177, v38, v39
	v_pk_mul_f32 v[56:57], v[82:83], s[50:51] op_sel_hi:[1,0]
	v_and_b32_e32 v69, 0xffff0000, v52
	s_waitcnt lgkmcnt(0)
	v_mfma_f32_32x32x16_bf16 v[32:47], v[76:79], v[174:177], v[16:31]
	v_cvt_pk_bf16_f32 v165, v56, v57
	ds_read_b128 v[56:59], v94 offset:2560
	ds_read_b128 v[64:67], v94 offset:2048
	v_lshlrev_b32_e32 v68, 16, v52
	v_mul_f32_e64 v68, v68, s50
	v_mul_f32_e64 v69, v69, s50
	v_cvt_pk_bf16_f32 v170, v68, v69
	v_and_b32_e32 v69, 0xffff0000, v53
	v_mfma_f32_32x32x16_bf16 v[16:31], v[72:75], v[174:177], v[16:31]
	v_lshlrev_b32_e32 v68, 16, v53
	v_mul_f32_e64 v52, v68, s50
	v_mul_f32_e64 v53, v69, s50
	v_cvt_pk_bf16_f32 v171, v52, v53
	v_and_b32_e32 v53, 0xffff0000, v54
	v_lshlrev_b32_e32 v52, 16, v54
	v_pk_mul_f32 v[52:53], v[52:53], s[50:51] op_sel_hi:[1,0]
	s_waitcnt lgkmcnt(0)
	v_mfma_f32_32x32x16_bf16 v[32:47], v[64:67], v[162:165], v[32:47]
	ds_read_b128 v[64:67], v94 offset:4608
	ds_read_b128 v[68:71], v94 offset:4096
	v_cvt_pk_bf16_f32 v172, v52, v53
	v_and_b32_e32 v53, 0xffff0000, v55
	v_lshlrev_b32_e32 v52, 16, v55
	v_pk_mul_f32 v[52:53], v[52:53], s[50:51] op_sel_hi:[1,0]
	s_nop 0
	v_cvt_pk_bf16_f32 v173, v52, v53
	v_mfma_f32_32x32x16_bf16 v[16:31], v[56:59], v[162:165], v[16:31]
	v_and_b32_e32 v53, 0xffff0000, v48
	v_lshlrev_b32_e32 v52, 16, v48
	v_mul_f32_e64 v52, v52, s50
	v_mul_f32_e64 v53, v53, s50
	v_cvt_pk_bf16_f32 v166, v52, v53
	v_and_b32_e32 v53, 0xffff0000, v49
	v_lshlrev_b32_e32 v52, 16, v49
	s_waitcnt lgkmcnt(0)
	v_mfma_f32_32x32x16_bf16 v[32:47], v[68:71], v[170:173], v[32:47]
	v_mul_f32_e64 v48, v52, s50
	v_mul_f32_e64 v49, v53, s50
	ds_read_b128 v[52:55], v94 offset:6656
	ds_read_b128 v[56:59], v94 offset:6144
	v_cvt_pk_bf16_f32 v167, v48, v49
	v_and_b32_e32 v49, 0xffff0000, v50
	v_lshlrev_b32_e32 v48, 16, v50
	v_pk_mul_f32 v[48:49], v[48:49], s[50:51] op_sel_hi:[1,0]
	v_mfma_f32_32x32x16_bf16 v[16:31], v[64:67], v[170:173], v[16:31]
	v_cvt_pk_bf16_f32 v168, v48, v49
	v_and_b32_e32 v49, 0xffff0000, v51
	v_lshlrev_b32_e32 v48, 16, v51
	v_mul_f32_e64 v48, v48, s50
	v_mul_f32_e64 v49, v49, s50
	v_cvt_pk_bf16_f32 v169, v48, v49
	v_lshlrev_b32_e32 v48, 4, v62
	v_and_b32_e32 v48, 0xc0, v48
	s_waitcnt lgkmcnt(0)
; #define WAIT_BAR(N) asm volatile("s_waitcnt vmcnt(" #N ") lgkmcnt(0)\n\ts_barrier":::"memory")
;   #define DMA_K(t,slot) glds16(ksrc+(long)(t)*KVBLK*DM,(unsigned)__builtin_amdgcn_readfirstlane(kdst+(slot)))
;   #define DMA_V(t,slot) do{ glds16(vsrc+(long)(t)*KVBLK*DM,(unsigned)__builtin_amdgcn_readfirstlane(vdst+VM*(slot))); \
;     if constexpr(DV==128){ glds16(vsrc+64+(long)(t)*KVBLK*DM,(unsigned)__builtin_amdgcn_readfirstlane(vdst+VM*(slot)+8192)); } }while(0)
;   #define WAIT_KV() do{ if constexpr(DV==128){WAIT_BAR(3);} else {WAIT_BAR(2);} }while(0)
;   #define CMASK(P0,P1,t) do{ if constexpr(WIN){ wmask(P0,P1,(t_lo+(t))*KVBLK+4*hi,qpos); } }while(0)
;   #define ROT() do{sl_prev=sl_cur;sl_cur=sl_next;sl_next=(sl_next==(NSLOT-1)*SLOTB)?0:sl_next+SLOTB;}while(0)
; template<int THRL,bool WIN,int DM,int ODM,int DV,int QMODE> __device__ __forceinline__ void attn_unit(const bf16*Qp,const bf16*__restrict__ Kp,const bf16*__restrict__ Vp,bf16*Op,const int q0,const int t_lo,const int NT,const float sink2,char*shm,const float*qgain,const float*qtab,const int b0,const ...
;     ...
;   qkt(pA0,pA1,Kbase+s0,qr,negm,r32,hi);asm volatile("s_nop 15\n\ts_nop 7":"+v"(pA0),"+v"(pA1));CMASK(pA0,pA1,0);
;   START(pA0,pA1);
;   _Pragma("unroll") for(int r=0;r<16;++r)pA1[r]=__builtin_amdgcn_exp2f(pA1[r]);
;   WAIT_BAR(0);
;   DMA_K(3,s0);DMA_V(1,s1);
;   ROT();
;   kload8(kf,kp0+sl_cur);
;   WAIT_KV();
	v_mfma_f32_32x32x16_bf16 v[32:47], v[56:59], v[166:169], v[32:47]
	v_lshl_or_b32 v221, v251, 8, v48
	v_add_u32_e32 v48, 0, v223
	v_add3_u32 v249, v48, v219, v221
	v_mfma_f32_32x32x16_bf16 v[16:31], v[52:55], v[166:169], v[16:31]
	s_nop 15
	s_nop 7
	s_nop 0
	v_max3_f32 v48, v32, v33, v16
	v_max3_f32 v49, v34, v35, v17
	s_nop 0
	v_max3_f32 v48, v48, v18, v19
	v_max3_f32 v49, v49, v38, v39
	s_nop 0
	v_max3_f32 v48, v48, v36, v37
	v_max3_f32 v49, v49, v22, v23
	s_nop 0
	v_max3_f32 v48, v48, v20, v21
	v_max3_f32 v49, v49, v42, v43
	s_nop 0
	v_max3_f32 v48, v48, v40, v41
	v_max3_f32 v49, v49, v26, v27
	s_nop 0
	v_max3_f32 v48, v48, v24, v25
	v_max3_f32 v49, v49, v46, v47
	s_nop 0
	v_max3_f32 v48, v48, v44, v45
	v_max3_f32 v49, v49, v30, v31
	s_nop 0
	v_max3_f32 v48, v48, v28, v29
	s_nop 0
	v_max_f32_e32 v48, v48, v49
	s_nop 0
	v_mov_b32_e32 v49, v48
	s_nop 1
	v_permlane32_swap_b32_e32 v48, v49
	v_max_f32_e32 v48, v48, v49
	s_nop 0
	v_add_f32_e32 v245, v0, v48
	v_sub_f32_e32 v49, v16, v48
	v_sub_f32_e32 v50, v17, v48
	v_lshl_add_u64 v[16:17], v[224:225], 0, s[56:57]
	v_xor_b32_e32 v66, 0x80000000, v245
	v_mov_b32_e32 v67, v66
	v_mov_b32_e32 v68, v66
	v_mov_b32_e32 v69, v66
	v_mov_b32_e32 v70, v66
	v_mov_b32_e32 v71, v66
	v_mov_b32_e32 v72, v66
	v_mov_b32_e32 v73, v66
	v_mov_b32_e32 v74, v66
	v_mov_b32_e32 v75, v66
	v_mov_b32_e32 v76, v66
	v_mov_b32_e32 v77, v66
	v_mov_b32_e32 v78, v66
	v_mov_b32_e32 v79, v66
	v_mov_b32_e32 v80, v66
	v_mov_b32_e32 v81, v66
	s_waitcnt vmcnt(0) lgkmcnt(0)
	s_barrier
	s_mov_b32 s6, m0
	s_mov_b32 m0, s2
	s_nop 0
	global_load_lds_dwordx4 v[16:17], off
	s_mov_b32 m0, s6
	s_lshl_b32 s2, s3, 1
	v_lshl_add_u64 v[16:17], v[226:227], 0, s[54:55]
	s_add_i32 s2, s64, s2
	s_mov_b32 s6, m0
	s_mov_b32 m0, s2
	s_nop 0
	global_load_lds_dwordx4 v[16:17], off
	s_mov_b32 m0, s6
	s_mov_b64 s[6:7], 0xe80
	v_lshl_add_u64 v[228:229], v[60:61], 0, s[6:7]
	s_mov_b64 s[6:7], 0x48080
	v_lshl_add_u64 v[16:17], v[226:227], 0, s[6:7]
	s_addk_i32 s2, 0x2000
	s_mov_b32 s6, m0
	s_mov_b32 m0, s2
	s_nop 0
	global_load_lds_dwordx4 v[16:17], off
	s_mov_b32 m0, s6
	v_add_u32_e32 v16, s3, v214
	ds_read_b128 v[206:209], v16
	ds_read_b128 v[202:205], v16 offset:512
	ds_read_b128 v[198:201], v16 offset:2048
	ds_read_b128 v[194:197], v16 offset:2560
	ds_read_b128 v[190:193], v16 offset:4096
	ds_read_b128 v[186:189], v16 offset:4608
	ds_read_b128 v[182:185], v16 offset:6144
	ds_read_b128 v[178:181], v16 offset:6656
	v_sub_f32_e32 v32, v32, v48
	v_sub_f32_e32 v33, v33, v48
	v_sub_f32_e32 v34, v34, v48
	v_sub_f32_e32 v18, v18, v48
	v_sub_f32_e32 v35, v35, v48
	v_sub_f32_e32 v19, v19, v48
	v_sub_f32_e32 v36, v36, v48
	v_sub_f32_e32 v20, v20, v48
	v_sub_f32_e32 v37, v37, v48
	v_sub_f32_e32 v21, v21, v48
	v_sub_f32_e32 v38, v38, v48
	v_sub_f32_e32 v22, v22, v48
	v_sub_f32_e32 v39, v39, v48
	v_sub_f32_e32 v23, v23, v48
	v_sub_f32_e32 v40, v40, v48
	v_sub_f32_e32 v24, v24, v48
	v_sub_f32_e32 v41, v41, v48
	v_sub_f32_e32 v25, v25, v48
	v_sub_f32_e32 v42, v42, v48
	v_sub_f32_e32 v26, v26, v48
	v_sub_f32_e32 v43, v43, v48
	v_sub_f32_e32 v27, v27, v48
	v_sub_f32_e32 v44, v44, v48
	v_sub_f32_e32 v28, v28, v48
	v_sub_f32_e32 v45, v45, v48
	v_sub_f32_e32 v29, v29, v48
	v_sub_f32_e32 v46, v46, v48
	v_sub_f32_e32 v30, v30, v48
	v_sub_f32_e32 v47, v47, v48
	v_sub_f32_e32 v31, v31, v48
	s_nop 0
	v_exp_f32_e32 v98, v32
	v_exp_f32_e32 v113, v47
	v_exp_f32_e32 v99, v33
	v_exp_f32_e32 v100, v34
	v_exp_f32_e32 v101, v35
	v_exp_f32_e32 v102, v36
	v_exp_f32_e32 v103, v37
	v_exp_f32_e32 v104, v38
	v_exp_f32_e32 v105, v39
	v_exp_f32_e32 v106, v40
	v_exp_f32_e32 v107, v41
	v_exp_f32_e32 v108, v42
	v_exp_f32_e32 v109, v43
	v_exp_f32_e32 v110, v44
	v_exp_f32_e32 v111, v45
	v_exp_f32_e32 v112, v46
	v_exp_f32_e32 v97, v31
	v_exp_f32_e32 v82, v49
	v_exp_f32_e32 v83, v50
	v_exp_f32_e32 v84, v18
	v_exp_f32_e32 v85, v19
	v_exp_f32_e32 v86, v20
	v_exp_f32_e32 v87, v21
	v_exp_f32_e32 v88, v22
	v_exp_f32_e32 v89, v23
	v_exp_f32_e32 v90, v24
	v_exp_f32_e32 v91, v25
	v_exp_f32_e32 v92, v26
	v_exp_f32_e32 v93, v27
	v_exp_f32_e32 v94, v28
	v_exp_f32_e32 v95, v29
	v_exp_f32_e32 v96, v30
	s_mov_b64 s[6:7], 0x120e80
	s_waitcnt vmcnt(3) lgkmcnt(0)
	s_barrier
	v_lshl_add_u64 v[232:233], v[60:61], 0, s[6:7]
	v_mov_b64_e32 v[64:65], v[14:15]
	v_mov_b64_e32 v[48:49], v[14:15]
	v_mov_b64_e32 v[32:33], v[14:15]
	v_mov_b64_e32 v[62:63], v[12:13]
	v_mov_b64_e32 v[60:61], v[10:11]
	v_mov_b64_e32 v[58:59], v[8:9]
	v_mov_b64_e32 v[56:57], v[6:7]
	v_mov_b64_e32 v[54:55], v[4:5]
	v_mov_b64_e32 v[52:53], v[2:3]
	v_mov_b64_e32 v[50:51], v[0:1]
	v_mov_b64_e32 v[46:47], v[12:13]
	v_mov_b64_e32 v[44:45], v[10:11]
	v_mov_b64_e32 v[42:43], v[8:9]
	v_mov_b64_e32 v[40:41], v[6:7]
	v_mov_b64_e32 v[38:39], v[4:5]
	v_mov_b64_e32 v[36:37], v[2:3]
	v_mov_b64_e32 v[34:35], v[0:1]
	v_mov_b64_e32 v[30:31], v[12:13]
	v_mov_b64_e32 v[28:29], v[10:11]
	v_mov_b64_e32 v[26:27], v[8:9]
	v_mov_b64_e32 v[24:25], v[6:7]
	v_mov_b64_e32 v[22:23], v[4:5]
	v_mov_b64_e32 v[20:21], v[2:3]
	v_mov_b64_e32 v[18:19], v[0:1]
	v_mov_b64_e32 v[16:17], v[14:15]
	s_mov_b64 s[6:7], 0
	v_mov_b64_e32 v[14:15], v[12:13]
	v_mov_b64_e32 v[12:13], v[10:11]
	v_mov_b64_e32 v[10:11], v[8:9]
	v_mov_b64_e32 v[8:9], v[6:7]
	v_mov_b64_e32 v[6:7], v[4:5]
	v_mov_b64_e32 v[4:5], v[2:3]
	v_mov_b64_e32 v[2:3], v[0:1]
	v_readfirstlane_b32 s98, v224
	v_readfirstlane_b32 s99, v225
	s_nop 1
	v_subrev_u32_e32 v234, s98, v224
	v_subrev_u32_e32 v236, s98, v226
	v_subrev_u32_e32 v238, s98, v228
	v_add_u32_e32 v235, 0x168000, v234
	v_add_u32_e32 v234, 0x120000, v234
	v_add_u32_e32 v237, 0xd8000, v236
	v_add_u32_e32 v236, 0x90000, v236
	v_add_u32_e32 v239, 0xd8000, v238
	v_add_u32_e32 v238, 0x90000, v238
	s_mov_b64 s[92:93], 0
.LBB0_465:
	s_lshl_b32 s2, s15, 1
	v_add_u32_e32 v216, s2, v249
	ds_read_b64_tr_b16 v[210:211], v216 offset:24576
	ds_read_b64_tr_b16 v[212:213], v216 offset:25088
	s_waitcnt lgkmcnt(9)
	v_mfma_f32_32x32x16_bf16 v[130:145], v[206:209], v[174:177], v[66:81]
	v_add_f32_e32 v1, v98, v99
	v_add_f32_e32 v1, v100, v1
	v_add_f32_e32 v1, v101, v1
	v_add_f32_e32 v1, v102, v1
	v_add_f32_e32 v1, v103, v1
	v_cvt_pk_bf16_f32 v158, v98, v99
	v_cvt_pk_bf16_f32 v159, v100, v101
	ds_read_b64_tr_b16 v[98:99], v216 offset:28672
	ds_read_b64_tr_b16 v[100:101], v216 offset:29184
	s_waitcnt lgkmcnt(10)
	v_mfma_f32_32x32x16_bf16 v[114:129], v[202:205], v[174:177], v[66:81]
	v_add_f32_e32 v1, v104, v1
	v_add_f32_e32 v1, v105, v1
	v_add_f32_e32 v1, v106, v1
	v_add_f32_e32 v1, v107, v1
	v_cvt_pk_bf16_f32 v160, v102, v103
	v_cvt_pk_bf16_f32 v161, v104, v105
	ds_read_b64_tr_b16 v[102:103], v216 offset:25600
	ds_read_b64_tr_b16 v[104:105], v216 offset:26112
	s_waitcnt lgkmcnt(11)
	v_mfma_f32_32x32x16_bf16 v[130:145], v[198:201], v[162:165], v[130:145]
	v_add_f32_e32 v1, v108, v1
	v_add_f32_e32 v1, v109, v1
	v_add_f32_e32 v1, v110, v1
	v_add_f32_e32 v1, v111, v1
	v_cvt_pk_bf16_f32 v154, v106, v107
	v_cvt_pk_bf16_f32 v155, v108, v109
	ds_read_b64_tr_b16 v[106:107], v216 offset:29696
	ds_read_b64_tr_b16 v[108:109], v216 offset:30208
	s_waitcnt lgkmcnt(12)
	v_mfma_f32_32x32x16_bf16 v[114:129], v[194:197], v[162:165], v[114:129]
	v_add_f32_e32 v1, v112, v1
	v_add_f32_e32 v1, v113, v1
	v_add_f32_e32 v1, v82, v1
	v_add_f32_e32 v1, v83, v1
	v_cvt_pk_bf16_f32 v156, v110, v111
	v_cvt_pk_bf16_f32 v157, v112, v113
	ds_read_b64_tr_b16 v[110:111], v216 offset:26624
	ds_read_b64_tr_b16 v[112:113], v216 offset:27136
	s_waitcnt lgkmcnt(13)
	v_mfma_f32_32x32x16_bf16 v[130:145], v[190:193], v[170:173], v[130:145]
	v_add_f32_e32 v1, v84, v1
	v_add_f32_e32 v1, v85, v1
	v_add_f32_e32 v1, v86, v1
	v_add_f32_e32 v1, v87, v1
	v_cvt_pk_bf16_f32 v150, v82, v83
	v_cvt_pk_bf16_f32 v151, v84, v85
	ds_read_b64_tr_b16 v[82:83], v216 offset:30720
	ds_read_b64_tr_b16 v[84:85], v216 offset:31232
	s_waitcnt lgkmcnt(14)
	v_mfma_f32_32x32x16_bf16 v[114:129], v[186:189], v[170:173], v[114:129]
	v_add_f32_e32 v1, v88, v1
	v_add_f32_e32 v1, v89, v1
	v_add_f32_e32 v1, v90, v1
	v_add_f32_e32 v1, v91, v1
	v_cvt_pk_bf16_f32 v152, v86, v87
	v_cvt_pk_bf16_f32 v153, v88, v89
	ds_read_b64_tr_b16 v[86:87], v216 offset:27648
	ds_read_b64_tr_b16 v[88:89], v216 offset:28160
	s_waitcnt lgkmcnt(14)
	v_mfma_f32_32x32x16_bf16 v[130:145], v[182:185], v[166:169], v[130:145]
	v_add_f32_e32 v1, v92, v1
	v_add_f32_e32 v1, v93, v1
	v_add_f32_e32 v1, v94, v1
	v_add_f32_e32 v1, v95, v1
	v_cvt_pk_bf16_f32 v146, v90, v91
	v_cvt_pk_bf16_f32 v147, v92, v93
	ds_read_b64_tr_b16 v[90:91], v216 offset:31744
	ds_read_b64_tr_b16 v[92:93], v216 offset:32256
	v_mfma_f32_32x32x16_bf16 v[114:129], v[178:181], v[166:169], v[114:129]
	v_add_f32_e32 v1, v96, v1
	v_add_f32_e32 v1, v97, v1
	v_cvt_pk_bf16_f32 v148, v94, v95
	v_cvt_pk_bf16_f32 v149, v96, v97
	s_add_i32 s2, s3, s47
	s_mov_b32 m0, s2
	s_nop 0
	global_load_lds_dwordx4 v234, s[98:99]
	s_lshl_b32 s51, s36, 1
	s_add_i32 s2, s51, s64
	s_mov_b32 m0, s2
	s_nop 0
	global_load_lds_dwordx4 v236, s[98:99]
	s_addk_i32 s2, 0x2000
	s_mov_b32 m0, s2
	s_nop 0
	global_load_lds_dwordx4 v238, s[98:99]
	v_max_f32_e32 v94, v130, v131
	v_max3_f32 v95, v132, v133, v115
	v_max3_f32 v94, v94, v114, v116
	v_max3_f32 v94, v94, v117, v134
	v_max3_f32 v95, v95, v136, v137
	v_max3_f32 v94, v94, v135, v118
	v_max3_f32 v95, v95, v120, v121
	v_max3_f32 v94, v94, v119, v138
	v_max3_f32 v95, v95, v140, v141
	v_max3_f32 v94, v94, v139, v122
	v_max3_f32 v95, v95, v124, v125
	v_max3_f32 v94, v94, v123, v142
	v_max3_f32 v95, v95, v144, v145
	v_max3_f32 v94, v94, v143, v126
	v_max3_f32 v95, v95, v128, v129
	v_max3_f32 v94, v94, v127, v95
	v_cmp_lt_f32_e32 vcc, s19, v94
	v_add_f32_e32 v1, v215, v1
	s_cbranch_vccnz .LBB0_473
.LBB0_466:
	s_waitcnt lgkmcnt(14)
	v_mfma_f32_32x32x16_bf16 v[50:65], v[158:161], v[210:213], v[50:65]
	v_exp_f32_e32 v130, v130
	v_exp_f32_e32 v131, v131
	ds_read_b64_tr_b16 v[94:95], v216 offset:32768
	ds_read_b64_tr_b16 v[96:97], v216 offset:33280
	s_waitcnt lgkmcnt(14)
	v_mfma_f32_32x32x16_bf16 v[34:49], v[158:161], v[98:101], v[34:49]
	v_exp_f32_e32 v132, v132
	v_exp_f32_e32 v133, v133
	ds_read_b64_tr_b16 v[98:99], v216 offset:36864
	ds_read_b64_tr_b16 v[100:101], v216 offset:37376
	s_waitcnt lgkmcnt(14)
	v_mfma_f32_32x32x16_bf16 v[50:65], v[154:157], v[102:105], v[50:65]
	v_exp_f32_e32 v134, v134
	v_exp_f32_e32 v135, v135
	ds_read_b64_tr_b16 v[102:103], v216 offset:33792
	ds_read_b64_tr_b16 v[104:105], v216 offset:34304
	s_waitcnt lgkmcnt(14)
	v_mfma_f32_32x32x16_bf16 v[34:49], v[154:157], v[106:109], v[34:49]
	v_exp_f32_e32 v136, v136
	v_exp_f32_e32 v137, v137
	ds_read_b64_tr_b16 v[106:107], v216 offset:37888
	ds_read_b64_tr_b16 v[108:109], v216 offset:38400
	s_waitcnt lgkmcnt(14)
	v_mfma_f32_32x32x16_bf16 v[50:65], v[150:153], v[110:113], v[50:65]
	v_exp_f32_e32 v138, v138
	v_exp_f32_e32 v139, v139
	ds_read_b64_tr_b16 v[110:111], v216 offset:34816
	ds_read_b64_tr_b16 v[112:113], v216 offset:35328
	s_waitcnt lgkmcnt(14)
	v_mfma_f32_32x32x16_bf16 v[34:49], v[150:153], v[82:85], v[34:49]
	v_exp_f32_e32 v140, v140
	v_exp_f32_e32 v141, v141
	ds_read_b64_tr_b16 v[190:191], v216 offset:38912
	ds_read_b64_tr_b16 v[192:193], v216 offset:39424
	s_waitcnt lgkmcnt(14)
	v_mfma_f32_32x32x16_bf16 v[50:65], v[146:149], v[86:89], v[50:65]
	v_exp_f32_e32 v142, v142
	v_exp_f32_e32 v143, v143
	ds_read_b64_tr_b16 v[86:87], v216 offset:35840
	ds_read_b64_tr_b16 v[88:89], v216 offset:36352
	s_waitcnt lgkmcnt(14)
;   #define WAIT_KV() do{ if constexpr(DV==128){WAIT_BAR(3);} else {WAIT_BAR(2);} }while(0)
;   #define RESC() do{ if(resc){ asm volatile("s_waitcnt lgkmcnt(0)":::"memory"); \
;       _Pragma("unroll") for(int d_=0;d_<DV/32;++d_) _Pragma("unroll") for(int r=0;r<16;++r)o[d_][r]*=wsf[crow(r,hi)]; } }while(0)
;   #define ROT() do{sl_prev=sl_cur;sl_cur=sl_next;sl_next=(sl_next==(NSLOT-1)*SLOTB)?0:sl_next+SLOTB;}while(0)
; template<int THRL,bool WIN,int DM,int ODM,int DV,int QMODE> __device__ __forceinline__ void attn_unit(const bf16*Qp,const bf16*__restrict__ Kp,const bf16*__restrict__ Vp,bf16*Op,const int q0,const int t_lo,const int NT,const float sink2,char*shm,const float*qgain,const float*qtab,const int b0,const ...
;     ...
;   int t=1;
;   for(;t+5<NT;t+=2){
;     STEP(pB0,pB1,pA0,pA1,t,true,true,true);     WAIT_KV(); RESC(); ROT();
	v_mfma_f32_32x32x16_bf16 v[34:49], v[146:149], v[90:93], v[34:49]
	v_exp_f32_e32 v144, v144
	v_exp_f32_e32 v145, v145
	ds_read_b64_tr_b16 v[90:91], v216 offset:39936
	ds_read_b64_tr_b16 v[92:93], v216 offset:40448
	s_waitcnt lgkmcnt(14)
	v_mfma_f32_32x32x16_bf16 v[18:33], v[158:161], v[94:97], v[18:33]
	v_exp_f32_e32 v114, v114
	v_exp_f32_e32 v115, v115
	s_waitcnt lgkmcnt(12)
	v_mfma_f32_32x32x16_bf16 v[2:17], v[158:161], v[98:101], v[2:17]
	v_exp_f32_e32 v116, v116
	v_exp_f32_e32 v117, v117
	v_add_u32_e32 v94, s36, v214
	ds_read_b128 v[82:85], v94
	ds_read_b128 v[202:205], v94 offset:512
	s_waitcnt lgkmcnt(12)
	v_mfma_f32_32x32x16_bf16 v[18:33], v[154:157], v[102:105], v[18:33]
	v_exp_f32_e32 v118, v118
	v_exp_f32_e32 v119, v119
	ds_read_b128 v[206:209], v94 offset:2048
	ds_read_b128 v[198:201], v94 offset:2560
	s_waitcnt lgkmcnt(12)
	v_mfma_f32_32x32x16_bf16 v[2:17], v[154:157], v[106:109], v[2:17]
	v_exp_f32_e32 v120, v120
	v_exp_f32_e32 v121, v121
	ds_read_b128 v[194:197], v94 offset:4096
	ds_read_b128 v[186:189], v94 offset:4608
	s_waitcnt lgkmcnt(12)
	v_mfma_f32_32x32x16_bf16 v[18:33], v[150:153], v[110:113], v[18:33]
	v_exp_f32_e32 v122, v122
	v_exp_f32_e32 v123, v123
	ds_read_b128 v[182:185], v94 offset:6144
	ds_read_b128 v[178:181], v94 offset:6656
	s_waitcnt lgkmcnt(12)
	v_mfma_f32_32x32x16_bf16 v[2:17], v[150:153], v[190:193], v[2:17]
	v_exp_f32_e32 v124, v124
	v_exp_f32_e32 v125, v125
	s_waitcnt lgkmcnt(10)
	v_mfma_f32_32x32x16_bf16 v[18:33], v[146:149], v[86:89], v[18:33]
	v_exp_f32_e32 v126, v126
	v_exp_f32_e32 v127, v127
	s_waitcnt lgkmcnt(8)
	v_mfma_f32_32x32x16_bf16 v[2:17], v[146:149], v[90:93], v[2:17]
	v_exp_f32_e32 v128, v128
	v_exp_f32_e32 v129, v129
	s_add_i32 s2, s36, 0x2000
	s_cmpk_lg_i32 s36, 0x4000
	s_cselect_b32 s14, s2, 0
	s_lshl_b32 s2, s3, 1
	s_cmp_lg_u32 s92, 0
	s_waitcnt vmcnt(3) lgkmcnt(0)
	s_barrier
	s_cbranch_scc0 .LBB0_468
	s_waitcnt lgkmcnt(0)
	v_add_u32_e32 v98, s65, v243
	ds_read_b128 v[86:89], v98 offset:96
	ds_read_b128 v[90:93], v98 offset:64
	ds_read_b128 v[94:97], v98 offset:32
	ds_read_b128 v[98:101], v98
	s_waitcnt lgkmcnt(3)
	v_pk_mul_f32 v[62:63], v[62:63], v[86:87]
	s_waitcnt lgkmcnt(2)
	v_pk_mul_f32 v[58:59], v[58:59], v[90:91]
	s_waitcnt lgkmcnt(1)
	v_pk_mul_f32 v[54:55], v[54:55], v[94:95]
	v_pk_mul_f32 v[64:65], v[64:65], v[88:89]
	v_pk_mul_f32 v[60:61], v[60:61], v[92:93]
	v_pk_mul_f32 v[56:57], v[56:57], v[96:97]
	s_waitcnt lgkmcnt(0)
	v_pk_mul_f32 v[52:53], v[52:53], v[100:101]
	v_pk_mul_f32 v[50:51], v[50:51], v[98:99]
	v_pk_mul_f32 v[46:47], v[46:47], v[86:87]
	v_pk_mul_f32 v[42:43], v[42:43], v[90:91]
	v_pk_mul_f32 v[38:39], v[38:39], v[94:95]
	v_pk_mul_f32 v[48:49], v[48:49], v[88:89]
	v_pk_mul_f32 v[44:45], v[44:45], v[92:93]
	v_pk_mul_f32 v[40:41], v[40:41], v[96:97]
	v_pk_mul_f32 v[36:37], v[36:37], v[100:101]
	v_pk_mul_f32 v[34:35], v[34:35], v[98:99]
	v_pk_mul_f32 v[30:31], v[30:31], v[86:87]
	v_pk_mul_f32 v[26:27], v[26:27], v[90:91]
	v_pk_mul_f32 v[22:23], v[22:23], v[94:95]
	v_pk_mul_f32 v[32:33], v[32:33], v[88:89]
	v_pk_mul_f32 v[28:29], v[28:29], v[92:93]
	v_pk_mul_f32 v[24:25], v[24:25], v[96:97]
	v_pk_mul_f32 v[20:21], v[20:21], v[100:101]
	v_pk_mul_f32 v[18:19], v[18:19], v[98:99]
	v_pk_mul_f32 v[14:15], v[14:15], v[86:87]
	v_pk_mul_f32 v[10:11], v[10:11], v[90:91]
	v_pk_mul_f32 v[6:7], v[6:7], v[94:95]
	v_pk_mul_f32 v[16:17], v[16:17], v[88:89]
	v_pk_mul_f32 v[12:13], v[12:13], v[92:93]
	v_pk_mul_f32 v[8:9], v[8:9], v[96:97]
	v_pk_mul_f32 v[4:5], v[4:5], v[100:101]
	v_pk_mul_f32 v[2:3], v[2:3], v[98:99]
	s_mov_b64 s[92:93], 0
.LBB0_468:
	v_add_u32_e32 v210, s2, v249
	ds_read_b64_tr_b16 v[190:191], v210 offset:24576
	ds_read_b64_tr_b16 v[192:193], v210 offset:25088
	s_waitcnt lgkmcnt(9)
	v_mfma_f32_32x32x16_bf16 v[98:113], v[82:85], v[174:177], v[66:81]
	v_add_f32_e32 v86, v130, v131
	v_add_f32_e32 v86, v132, v86
	v_add_f32_e32 v86, v133, v86
	v_add_f32_e32 v86, v134, v86
	v_add_f32_e32 v86, v135, v86
	v_cvt_pk_bf16_f32 v158, v130, v131
	v_cvt_pk_bf16_f32 v159, v132, v133
	ds_read_b64_tr_b16 v[130:131], v210 offset:28672
	ds_read_b64_tr_b16 v[132:133], v210 offset:29184
	v_add_f32_e32 v82, v136, v86
	v_add_f32_e32 v82, v137, v82
	v_add_f32_e32 v82, v138, v82
	v_add_f32_e32 v146, v139, v82
	s_waitcnt lgkmcnt(10)
	v_mfma_f32_32x32x16_bf16 v[82:97], v[202:205], v[174:177], v[66:81]
	v_cvt_pk_bf16_f32 v160, v134, v135
	v_cvt_pk_bf16_f32 v161, v136, v137
	ds_read_b64_tr_b16 v[134:135], v210 offset:25600
	ds_read_b64_tr_b16 v[136:137], v210 offset:26112
	s_waitcnt lgkmcnt(11)
	v_mfma_f32_32x32x16_bf16 v[98:113], v[206:209], v[162:165], v[98:113]
	v_add_f32_e32 v146, v140, v146
	v_add_f32_e32 v146, v141, v146
	v_add_f32_e32 v146, v142, v146
	v_add_f32_e32 v146, v143, v146
	v_cvt_pk_bf16_f32 v154, v138, v139
	v_cvt_pk_bf16_f32 v155, v140, v141
	ds_read_b64_tr_b16 v[138:139], v210 offset:29696
	ds_read_b64_tr_b16 v[140:141], v210 offset:30208
	s_waitcnt lgkmcnt(12)
	v_mfma_f32_32x32x16_bf16 v[82:97], v[198:201], v[162:165], v[82:97]
	v_add_f32_e32 v146, v144, v146
	v_add_f32_e32 v146, v145, v146
	v_add_f32_e32 v146, v114, v146
	v_add_f32_e32 v146, v115, v146
	v_cvt_pk_bf16_f32 v156, v142, v143
	v_cvt_pk_bf16_f32 v157, v144, v145
	ds_read_b64_tr_b16 v[142:143], v210 offset:26624
	ds_read_b64_tr_b16 v[144:145], v210 offset:27136
	s_waitcnt lgkmcnt(13)
	v_mfma_f32_32x32x16_bf16 v[98:113], v[194:197], v[170:173], v[98:113]
	v_add_f32_e32 v146, v116, v146
	v_add_f32_e32 v146, v117, v146
	v_add_f32_e32 v146, v118, v146
	v_add_f32_e32 v146, v119, v146
	v_cvt_pk_bf16_f32 v150, v114, v115
	v_cvt_pk_bf16_f32 v151, v116, v117
	ds_read_b64_tr_b16 v[114:115], v210 offset:30720
	ds_read_b64_tr_b16 v[116:117], v210 offset:31232
	s_waitcnt lgkmcnt(14)
	v_mfma_f32_32x32x16_bf16 v[82:97], v[186:189], v[170:173], v[82:97]
	v_add_f32_e32 v146, v120, v146
	v_add_f32_e32 v146, v121, v146
	v_add_f32_e32 v146, v122, v146
	v_add_f32_e32 v146, v123, v146
	v_cvt_pk_bf16_f32 v152, v118, v119
	v_cvt_pk_bf16_f32 v153, v120, v121
	ds_read_b64_tr_b16 v[118:119], v210 offset:27648
	ds_read_b64_tr_b16 v[120:121], v210 offset:28160
	s_waitcnt lgkmcnt(14)
	v_mfma_f32_32x32x16_bf16 v[98:113], v[182:185], v[166:169], v[98:113]
	v_add_f32_e32 v146, v124, v146
	v_add_f32_e32 v146, v125, v146
	v_add_f32_e32 v146, v126, v146
	v_add_f32_e32 v182, v127, v146
	v_cvt_pk_bf16_f32 v146, v122, v123
	v_cvt_pk_bf16_f32 v147, v124, v125
	ds_read_b64_tr_b16 v[122:123], v210 offset:31744
	ds_read_b64_tr_b16 v[124:125], v210 offset:32256
	v_mfma_f32_32x32x16_bf16 v[82:97], v[178:181], v[166:169], v[82:97]
	v_add_f32_e32 v148, v128, v182
	v_add_f32_e32 v178, v129, v148
	v_cvt_pk_bf16_f32 v148, v126, v127
	v_cvt_pk_bf16_f32 v149, v128, v129
	s_add_i32 s2, s36, s47
	s_mov_b32 m0, s2
	s_nop 0
	global_load_lds_dwordx4 v235, s[98:99]
	s_lshl_b32 s2, s14, 1
	s_add_i32 s2, s2, s64
	s_mov_b32 m0, s2
	s_nop 0
	global_load_lds_dwordx4 v237, s[98:99]
	s_addk_i32 s2, 0x2000
	s_mov_b32 m0, s2
	s_nop 0
	global_load_lds_dwordx4 v239, s[98:99]
	v_max_f32_e32 v126, v98, v99
	v_max3_f32 v127, v100, v101, v83
	v_max3_f32 v126, v126, v82, v84
	v_max3_f32 v126, v126, v85, v102
	v_max3_f32 v127, v127, v104, v105
	v_max3_f32 v126, v126, v103, v86
	v_max3_f32 v127, v127, v88, v89
	v_max3_f32 v126, v126, v87, v106
	v_max3_f32 v127, v127, v108, v109
	v_max3_f32 v126, v126, v107, v90
	v_max3_f32 v127, v127, v92, v93
	v_max3_f32 v126, v126, v91, v110
	v_max3_f32 v127, v127, v112, v113
	v_max3_f32 v126, v126, v111, v94
	v_max3_f32 v127, v127, v96, v97
	v_add_f32_e32 v215, v1, v178
	v_max3_f32 v1, v126, v95, v127
	v_cmp_lt_f32_e32 vcc, s19, v1
	s_cbranch_vccnz .LBB0_476

;   #define WAIT_KV() do{ if constexpr(DV==128){WAIT_BAR(3);} else {WAIT_BAR(2);} }while(0)
;   #define RESC() do{ if(resc){ asm volatile("s_waitcnt lgkmcnt(0)":::"memory"); \
;       _Pragma("unroll") for(int d_=0;d_<DV/32;++d_) _Pragma("unroll") for(int r=0;r<16;++r)o[d_][r]*=wsf[crow(r,hi)]; } }while(0)
;   #define ROT() do{sl_prev=sl_cur;sl_cur=sl_next;sl_next=(sl_next==(NSLOT-1)*SLOTB)?0:sl_next+SLOTB;}while(0)
; template<int THRL,bool WIN,int DM,int ODM,int DV,int QMODE> __device__ __forceinline__ void attn_unit(const bf16*Qp,const bf16*__restrict__ Kp,const bf16*__restrict__ Vp,bf16*Op,const int q0,const int t_lo,const int NT,const float sink2,char*shm,const float*qgain,const float*qtab,const int b0,const ...
;     ...
;   f32x16 pA0,pA1,pB0,pB1;
;   int sl_prev=s0,sl_cur=s0,sl_next=s1;
;     ...
;   for(;t+5<NT;t+=2){
;     STEP(pB0,pB1,pA0,pA1,t,true,true,true);     WAIT_KV(); RESC(); ROT();
;     STEP(pA0,pA1,pB0,pB1,t+1,true,true,true);   WAIT_KV(); RESC(); ROT();
;   }
.LBB0_471:
	s_add_i32 s13, s13, 2
	s_add_i32 s2, s14, 0x2000
	s_cmpk_lg_i32 s14, 0x4000
	s_cselect_b32 s2, s2, 0
	s_add_u32 s6, s6, 0x90000
	s_addc_u32 s7, s7, 0
	s_add_u32 s98, s98, 0x90000
	s_addc_u32 s99, s99, 0
	s_add_i32 s3, s96, 2
	s_cmp_ge_u32 s13, s24
	s_cbranch_scc1 .Lmy_b_exitbar
	s_mov_b32 s96, s3
	s_mov_b32 s15, s36
	s_mov_b32 s3, s14
	s_mov_b32 s36, s2
	s_cmp_lg_u32 s92, 0
	s_waitcnt vmcnt(3) lgkmcnt(0)
	s_barrier
	s_cbranch_scc0 .LBB0_465
	s_waitcnt lgkmcnt(0)
	v_add_u32_e32 v1, s65, v243
	ds_read_b128 v[114:117], v1 offset:96
	ds_read_b128 v[118:121], v1 offset:64
	ds_read_b128 v[122:125], v1 offset:32
	ds_read_b128 v[126:129], v1
	s_waitcnt lgkmcnt(3)
	v_pk_mul_f32 v[62:63], v[62:63], v[114:115]
	s_waitcnt lgkmcnt(2)
	v_pk_mul_f32 v[58:59], v[58:59], v[118:119]
	s_waitcnt lgkmcnt(1)
	v_pk_mul_f32 v[54:55], v[54:55], v[122:123]
	v_pk_mul_f32 v[64:65], v[64:65], v[116:117]
	v_pk_mul_f32 v[60:61], v[60:61], v[120:121]
	v_pk_mul_f32 v[56:57], v[56:57], v[124:125]
	s_waitcnt lgkmcnt(0)
	v_pk_mul_f32 v[52:53], v[52:53], v[128:129]
	v_pk_mul_f32 v[50:51], v[50:51], v[126:127]
	v_pk_mul_f32 v[46:47], v[46:47], v[114:115]
	v_pk_mul_f32 v[42:43], v[42:43], v[118:119]
	v_pk_mul_f32 v[38:39], v[38:39], v[122:123]
	v_pk_mul_f32 v[48:49], v[48:49], v[116:117]
	v_pk_mul_f32 v[44:45], v[44:45], v[120:121]
	v_pk_mul_f32 v[40:41], v[40:41], v[124:125]
	v_pk_mul_f32 v[36:37], v[36:37], v[128:129]
	v_pk_mul_f32 v[34:35], v[34:35], v[126:127]
	v_pk_mul_f32 v[30:31], v[30:31], v[114:115]
	v_pk_mul_f32 v[26:27], v[26:27], v[118:119]
	v_pk_mul_f32 v[22:23], v[22:23], v[122:123]
	v_pk_mul_f32 v[32:33], v[32:33], v[116:117]
	v_pk_mul_f32 v[28:29], v[28:29], v[120:121]
	v_pk_mul_f32 v[24:25], v[24:25], v[124:125]
	v_pk_mul_f32 v[20:21], v[20:21], v[128:129]
	v_pk_mul_f32 v[18:19], v[18:19], v[126:127]
	v_pk_mul_f32 v[14:15], v[14:15], v[114:115]
	v_pk_mul_f32 v[10:11], v[10:11], v[118:119]
	v_pk_mul_f32 v[6:7], v[6:7], v[122:123]
	v_pk_mul_f32 v[16:17], v[16:17], v[116:117]
	v_pk_mul_f32 v[12:13], v[12:13], v[120:121]
	v_pk_mul_f32 v[8:9], v[8:9], v[124:125]
	v_pk_mul_f32 v[4:5], v[4:5], v[128:129]
	v_pk_mul_f32 v[2:3], v[2:3], v[126:127]
	s_mov_b64 s[92:93], 0
	s_branch .LBB0_465
.Lmy_b_exitbar:
	s_cmp_lg_u32 s92, 0
	s_waitcnt vmcnt(3) lgkmcnt(0)
	s_barrier
	s_cbranch_scc0 .Lmy_b_exit
	s_waitcnt lgkmcnt(0)
	v_add_u32_e32 v1, s65, v243
	ds_read_b128 v[114:117], v1 offset:96
	ds_read_b128 v[118:121], v1 offset:64
	ds_read_b128 v[122:125], v1 offset:32
	ds_read_b128 v[126:129], v1
	s_waitcnt lgkmcnt(3)
	v_pk_mul_f32 v[62:63], v[62:63], v[114:115]
	s_waitcnt lgkmcnt(2)
	v_pk_mul_f32 v[58:59], v[58:59], v[118:119]
	s_waitcnt lgkmcnt(1)
	v_pk_mul_f32 v[54:55], v[54:55], v[122:123]
	v_pk_mul_f32 v[64:65], v[64:65], v[116:117]
	v_pk_mul_f32 v[60:61], v[60:61], v[120:121]
	v_pk_mul_f32 v[56:57], v[56:57], v[124:125]
	s_waitcnt lgkmcnt(0)
	v_pk_mul_f32 v[52:53], v[52:53], v[128:129]
	v_pk_mul_f32 v[50:51], v[50:51], v[126:127]
	v_pk_mul_f32 v[46:47], v[46:47], v[114:115]
	v_pk_mul_f32 v[42:43], v[42:43], v[118:119]
	v_pk_mul_f32 v[38:39], v[38:39], v[122:123]
	v_pk_mul_f32 v[48:49], v[48:49], v[116:117]
	v_pk_mul_f32 v[44:45], v[44:45], v[120:121]
	v_pk_mul_f32 v[40:41], v[40:41], v[124:125]
	v_pk_mul_f32 v[36:37], v[36:37], v[128:129]
	v_pk_mul_f32 v[34:35], v[34:35], v[126:127]
	v_pk_mul_f32 v[30:31], v[30:31], v[114:115]
	v_pk_mul_f32 v[26:27], v[26:27], v[118:119]
	v_pk_mul_f32 v[22:23], v[22:23], v[122:123]
	v_pk_mul_f32 v[32:33], v[32:33], v[116:117]
	v_pk_mul_f32 v[28:29], v[28:29], v[120:121]
	v_pk_mul_f32 v[24:25], v[24:25], v[124:125]
	v_pk_mul_f32 v[20:21], v[20:21], v[128:129]
	v_pk_mul_f32 v[18:19], v[18:19], v[126:127]
	v_pk_mul_f32 v[14:15], v[14:15], v[114:115]
	v_pk_mul_f32 v[10:11], v[10:11], v[118:119]
	v_pk_mul_f32 v[6:7], v[6:7], v[122:123]
	v_pk_mul_f32 v[16:17], v[16:17], v[116:117]
	v_pk_mul_f32 v[12:13], v[12:13], v[120:121]
	v_pk_mul_f32 v[8:9], v[8:9], v[124:125]
	v_pk_mul_f32 v[4:5], v[4:5], v[128:129]
	v_pk_mul_f32 v[2:3], v[2:3], v[126:127]
	s_mov_b64 s[92:93], 0

.LBB0_473:
	s_mov_b64 s[92:93], -1
	v_mov_b32_e32 v95, v94
	s_nop 1
	v_permlane32_swap_b32_e32 v94, v95
	v_max_f32_e32 v94, v94, v95
	v_max_f32_e32 v66, v94, v94
	v_max_f32_e32 v94, 0, v66
	v_exp_f32_e64 v95, -v94
	v_add_f32_e32 v245, v245, v94
	v_xor_b32_e32 v66, 0x80000000, v245
	v_mov_b32_e32 v67, v66
	v_mov_b32_e32 v68, v66
	v_mov_b32_e32 v69, v66
	v_mov_b32_e32 v70, v66
	v_mov_b32_e32 v71, v66
	v_mov_b32_e32 v72, v66
	v_mov_b32_e32 v73, v66
	v_mov_b32_e32 v74, v66
	v_mov_b32_e32 v75, v66
	v_mov_b32_e32 v76, v66
	v_mov_b32_e32 v77, v66
	v_mov_b32_e32 v78, v66
	v_mov_b32_e32 v79, v66
	v_mov_b32_e32 v80, v66
	v_mov_b32_e32 v81, v66
	s_and_saveexec_b64 s[20:21], s[4:5]
	ds_write_b32 v242, v95
	s_or_b64 exec, exec, s[20:21]
	v_sub_f32_e32 v145, v145, v94
	v_sub_f32_e32 v144, v144, v94
	v_sub_f32_e32 v143, v143, v94
	v_sub_f32_e32 v142, v142, v94
	v_sub_f32_e32 v141, v141, v94
	v_sub_f32_e32 v140, v140, v94
	v_sub_f32_e32 v139, v139, v94
	v_sub_f32_e32 v138, v138, v94
	v_sub_f32_e32 v137, v137, v94
	v_sub_f32_e32 v136, v136, v94
	v_sub_f32_e32 v135, v135, v94
	v_sub_f32_e32 v134, v134, v94
	v_sub_f32_e32 v133, v133, v94
	v_sub_f32_e32 v132, v132, v94
	v_sub_f32_e32 v131, v131, v94
	v_sub_f32_e32 v130, v130, v94
	v_sub_f32_e32 v129, v129, v94
	v_sub_f32_e32 v128, v128, v94
	v_sub_f32_e32 v127, v127, v94
	v_sub_f32_e32 v126, v126, v94
	v_sub_f32_e32 v125, v125, v94
	v_sub_f32_e32 v124, v124, v94
	v_sub_f32_e32 v123, v123, v94
	v_sub_f32_e32 v122, v122, v94
	v_sub_f32_e32 v121, v121, v94
	v_sub_f32_e32 v120, v120, v94
	v_sub_f32_e32 v119, v119, v94
	v_sub_f32_e32 v118, v118, v94
	v_sub_f32_e32 v117, v117, v94
	v_sub_f32_e32 v116, v116, v94
	v_sub_f32_e32 v115, v115, v94
	v_sub_f32_e32 v114, v114, v94
	v_mul_f32_e32 v1, v1, v95
	s_branch .LBB0_466
.LBB0_476:
	s_mov_b64 s[92:93], -1
	v_mov_b32_e32 v126, v1
	s_nop 1
	v_permlane32_swap_b32_e32 v1, v126
	v_max_f32_e32 v1, v1, v126
	v_max_f32_e32 v1, v1, v1
	v_max_f32_e32 v1, 0, v1
	v_exp_f32_e64 v126, -v1
	v_add_f32_e32 v245, v245, v1
	v_xor_b32_e32 v66, 0x80000000, v245
	v_mov_b32_e32 v67, v66
	v_mov_b32_e32 v68, v66
	v_mov_b32_e32 v69, v66
	v_mov_b32_e32 v70, v66
	v_mov_b32_e32 v71, v66
	v_mov_b32_e32 v72, v66
	v_mov_b32_e32 v73, v66
	v_mov_b32_e32 v74, v66
	v_mov_b32_e32 v75, v66
	v_mov_b32_e32 v76, v66
	v_mov_b32_e32 v77, v66
	v_mov_b32_e32 v78, v66
	v_mov_b32_e32 v79, v66
	v_mov_b32_e32 v80, v66
	v_mov_b32_e32 v81, v66
	s_and_saveexec_b64 s[20:21], s[4:5]
	ds_write_b32 v242, v126
	s_or_b64 exec, exec, s[20:21]
	v_sub_f32_e32 v113, v113, v1
	v_sub_f32_e32 v112, v112, v1
	v_sub_f32_e32 v111, v111, v1
	v_sub_f32_e32 v110, v110, v1
	v_sub_f32_e32 v109, v109, v1
	v_sub_f32_e32 v108, v108, v1
	v_sub_f32_e32 v107, v107, v1
	v_sub_f32_e32 v106, v106, v1
	v_sub_f32_e32 v105, v105, v1
	v_sub_f32_e32 v104, v104, v1
	v_sub_f32_e32 v103, v103, v1
	v_sub_f32_e32 v102, v102, v1
	v_sub_f32_e32 v101, v101, v1
	v_sub_f32_e32 v100, v100, v1
	v_sub_f32_e32 v99, v99, v1
	v_sub_f32_e32 v98, v98, v1
	v_sub_f32_e32 v97, v97, v1
	v_sub_f32_e32 v96, v96, v1
	v_sub_f32_e32 v95, v95, v1
	v_sub_f32_e32 v94, v94, v1
	v_sub_f32_e32 v93, v93, v1
	v_sub_f32_e32 v92, v92, v1
	v_sub_f32_e32 v91, v91, v1
	v_sub_f32_e32 v90, v90, v1
	v_sub_f32_e32 v89, v89, v1
	v_sub_f32_e32 v88, v88, v1
	v_sub_f32_e32 v87, v87, v1
	v_sub_f32_e32 v86, v86, v1
	v_sub_f32_e32 v85, v85, v1
	v_sub_f32_e32 v84, v84, v1
	v_sub_f32_e32 v83, v83, v1
	v_sub_f32_e32 v82, v82, v1
	v_mul_f32_e32 v215, v215, v126
	s_branch .LBB0_469
